# diff-attn uniform-bias tiles take a fast path: 4 query-subtile scale+rowmax chains interleaved, one combined rescale check, rare rescale out of line
# speedup vs baseline: 1.0734x; 1.0136x over previous
; template <int DQK, bool BIAS>
; __device__ __forceinline__ void attn_pass(const hf* __restrict__ Q, int ldq, const hf* __restrict__ Kp, int ldk, const hf* __restrict__ VT,
;                                           int s0, int L, int q0, float scale_l2, const float* sBias, f4 (&oacc)[8][4], char* smem) {
;     ...
;     bool uni = true; float add = 0.f;
;     if (BIAS) {
;       const int dmin = key0 - (q0 + 255), dmax = key0 + 63 - q0;
;       uni = (dmax <= -91) || (dmin >= 91);
;       add = dmax <= -91 ? sBias[0] : sBias[256];
;     }
; #pragma unroll
;     for (int nq = 0; nq < 4; ++nq) {
;       if (BIAS) {
;         if (uni) {
; #pragma unroll
;           for (int mk = 0; mk < 4; ++mk)
; #pragma unroll
;             for (int j = 0; j < 4; ++j) sacc[mk][nq][j] = sacc[mk][nq][j] * scale_l2 + add;
;         } else {
; #pragma unroll
;           for (int mk = 0; mk < 4; ++mk)
; #pragma unroll
;             for (int j = 0; j < 4; ++j) {
;               int rel = (key0 + mk * 16 + fq * 4 + j) - (q0 + wv * 64 + nq * 16 + fr);
;               rel = min(max(rel, -128), 128);
;               sacc[mk][nq][j] = sacc[mk][nq][j] * scale_l2 + sBias[rel + 128];
;             }
;         }
.LBB0_1952:
	s_add_i32 s16, s93, s20
	s_add_i32 s17, s16, 0xffffff80
	s_addk_i32 s16, 0xfe26
	s_cmp_gt_u32 s16, 0xfffffe0c
	s_cselect_b64 s[26:27], -1, 0
	s_cmpk_lt_i32 s17, 0xff67
	s_mov_b32 s17, 0xfc00
	s_cselect_b32 s17, 0xf800, s17
	s_add_i32 s17, s17, 16
	v_mov_b32_e32 v32, s17
	ds_read_b32 v196, v32
	v_add_u32_e32 v252, s20, v241
	s_cmp_lt_u32 s16, 0xfffffe0d
	s_cbranch_scc1 .Lattn_fast
	s_mov_b64 s[16:17], -1
	v_add_u32_e32 v251, 0xffffff80, v252
	v_add_u32_e32 v250, 0xffffff81, v252
	v_add_u32_e32 v249, 0xffffff82, v252
	v_add_u32_e32 v248, 0xffffff83, v252
	v_add_u32_e32 v229, 0xffffff90, v252
	v_add_u32_e32 v228, 0xffffff91, v252
	v_add_u32_e32 v227, 0xffffff92, v252
	v_add_u32_e32 v230, 0xffffff93, v252
	v_add_u32_e32 v222, 0xffffffa0, v252
	v_add_u32_e32 v195, 0xffffffa1, v252
	v_add_u32_e32 v194, 0xffffffa2, v252
	v_add_u32_e32 v225, 0xffffffa3, v252
	v_med3_i32 v32, v251, s2, v223
	v_med3_i32 v33, v250, s2, v223
	v_med3_i32 v34, v249, s2, v223
	v_med3_i32 v35, v248, s2, v223
	v_med3_i32 v36, v229, s2, v223
	v_med3_i32 v37, v228, s2, v223
	v_med3_i32 v38, v227, s2, v223
	v_med3_i32 v39, v230, s2, v223
	v_med3_i32 v40, v222, s2, v223
	v_med3_i32 v41, v195, s2, v223
	v_med3_i32 v42, v194, s2, v223
	v_med3_i32 v43, v225, s2, v223
	v_add_u32_e32 v44, 0xffffffb0, v252
	v_add_u32_e32 v45, 0xffffffb1, v252
	v_add_u32_e32 v46, 0xffffffb2, v252
	v_add_u32_e32 v47, 0xffffffb3, v252
	v_lshl_add_u32 v32, v32, 2, 16
	v_lshl_add_u32 v33, v33, 2, 16
	v_lshl_add_u32 v34, v34, 2, 16
	v_lshl_add_u32 v35, v35, 2, 16
	v_lshl_add_u32 v36, v36, 2, 16
	v_lshl_add_u32 v37, v37, 2, 16
	v_lshl_add_u32 v38, v38, 2, 16
	v_lshl_add_u32 v39, v39, 2, 16
	v_lshl_add_u32 v40, v40, 2, 16
	v_lshl_add_u32 v41, v41, 2, 16
	v_lshl_add_u32 v42, v42, 2, 16
	v_lshl_add_u32 v43, v43, 2, 16
	v_med3_i32 v44, v44, s2, v223
	v_med3_i32 v45, v45, s2, v223
	v_med3_i32 v46, v46, s2, v223
	v_med3_i32 v47, v47, s2, v223
	ds_read_b32 v32, v32 offset:64000
	ds_read_b32 v33, v33 offset:64000
	ds_read_b32 v34, v34 offset:64000
	ds_read_b32 v35, v35 offset:64000
	ds_read_b32 v36, v36 offset:64000
	ds_read_b32 v37, v37 offset:64000
	ds_read_b32 v38, v38 offset:64000
	ds_read_b32 v39, v39 offset:64000
	v_lshl_add_u32 v44, v44, 2, 16
	v_lshl_add_u32 v45, v45, 2, 16
	v_lshl_add_u32 v46, v46, 2, 16
	v_lshl_add_u32 v47, v47, 2, 16
	ds_read_b32 v40, v40 offset:64000
	ds_read_b32 v41, v41 offset:64000
	ds_read_b32 v42, v42 offset:64000
	ds_read_b32 v43, v43 offset:64000
	ds_read_b32 v202, v44 offset:64000
	ds_read_b32 v203, v45 offset:64000
	ds_read_b32 v204, v46 offset:64000
	ds_read_b32 v205, v47 offset:64000
	s_waitcnt lgkmcnt(12)
	v_pk_fma_f32 v[34:35], v[190:191], s[22:23], v[34:35] op_sel_hi:[1,0,1]
	v_pk_fma_f32 v[32:33], v[188:189], s[22:23], v[32:33] op_sel_hi:[1,0,1]
	s_waitcnt lgkmcnt(8)
	v_pk_fma_f32 v[46:47], v[186:187], s[22:23], v[38:39] op_sel_hi:[1,0,1]
	v_pk_fma_f32 v[44:45], v[184:185], s[22:23], v[36:37] op_sel_hi:[1,0,1]
	s_waitcnt lgkmcnt(4)
	v_pk_fma_f32 v[42:43], v[182:183], s[22:23], v[42:43] op_sel_hi:[1,0,1]
	v_pk_fma_f32 v[40:41], v[180:181], s[22:23], v[40:41] op_sel_hi:[1,0,1]
	s_waitcnt lgkmcnt(0)
	v_pk_fma_f32 v[38:39], v[178:179], s[22:23], v[204:205] op_sel_hi:[1,0,1]
	v_pk_fma_f32 v[36:37], v[176:177], s[22:23], v[202:203] op_sel_hi:[1,0,1]
	s_mov_b64 s[16:17], 0

; DI float max3_(float a, float b, float c) { float r; asm("v_max3_f32 %0, %1, %2, %3" : "=v"(r) : "v"(a), "v"(b), "v"(c)); return r; }
; template <int DQK, bool BIAS>
; __device__ __forceinline__ void attn_pass(const hf* __restrict__ Q, int ldq, const hf* __restrict__ Kp, int ldk, const hf* __restrict__ VT,
;                                           int s0, int L, int q0, float scale_l2, const float* sBias, f4 (&oacc)[8][4], char* smem) {
;     ...
;       float mx = -1e30f;
; #pragma unroll
;       for (int mk = 0; mk < 4; ++mk) { mx = max3_(mx, sacc[mk][nq][0], sacc[mk][nq][1]); mx = max3_(mx, sacc[mk][nq][2], sacc[mk][nq][3]); }
;       mx = max3_(mx, shx(mx, 16), mx); mx = max3_(mx, shx(mx, 32), mx);
;       if (!BIAS) mx *= scale_l2;
;       const bool upd = mx > mrun[nq] + 8.f;
;       const float mnew = upd ? mx : mrun[nq];
;       if (__builtin_amdgcn_ballot_w64(upd) != 0) {
;         const float alpha = __builtin_amdgcn_exp2f(mrun[nq] - mnew);
;         lrun[nq] *= alpha;
; #pragma unroll
;         for (int md = 0; md < 8; ++md) { oacc[md][nq][0] *= alpha; oacc[md][nq][1] *= alpha; oacc[md][nq][2] *= alpha; oacc[md][nq][3] *= alpha; }
;       }
.LBB0_1974:
	v_max3_f32 v112, v199, v96, v97
	v_max3_f32 v112, v112, v98, v99
	v_max3_f32 v112, v112, v104, v105
	v_max3_f32 v112, v112, v106, v107
	v_max3_f32 v112, v112, v100, v101
	v_max3_f32 v112, v112, v102, v103
	v_max3_f32 v112, v112, v108, v109
	v_max3_f32 v112, v112, v110, v111
	v_mov_b32_e32 v113, v112
	s_nop 1
	v_permlane16_swap_b32_e32 v113, v112
	v_max_f32_e32 v112, v112, v113
	v_mov_b32_e32 v113, v112
	s_nop 1
	v_permlane32_swap_b32_e32 v113, v112
	v_max_f32_e32 v112, v112, v113
	v_add_f32_e32 v113, 0x41000000, v246
	v_cmp_gt_f32_e32 vcc, v112, v113
	s_nop 1
	v_cndmask_b32_e32 v112, v246, v112, vcc
	s_cbranch_vccz .LBB0_1976
	v_accvgpr_read_b32 v55, a115
	v_accvgpr_read_b32 v51, a127
	v_accvgpr_read_b32 v59, a99
	v_accvgpr_read_b32 v63, a83
	v_accvgpr_read_b32 v64, a60
	v_accvgpr_read_b32 v72, a48
	v_accvgpr_read_b32 v68, a32
	v_accvgpr_read_b32 v76, a20
	v_accvgpr_read_b32 v50, a126
	v_accvgpr_read_b32 v49, a125
	v_accvgpr_read_b32 v48, a124
	v_accvgpr_read_b32 v54, a114
	v_accvgpr_read_b32 v53, a113
	v_accvgpr_read_b32 v52, a112
	v_accvgpr_read_b32 v58, a98
	v_accvgpr_read_b32 v57, a97
	v_accvgpr_read_b32 v56, a96
	v_accvgpr_read_b32 v62, a82
	v_accvgpr_read_b32 v61, a81
	v_accvgpr_read_b32 v60, a80
	v_accvgpr_read_b32 v65, a61
	v_accvgpr_read_b32 v66, a62
	v_accvgpr_read_b32 v67, a63
	v_accvgpr_read_b32 v73, a49
	v_accvgpr_read_b32 v74, a50
	v_accvgpr_read_b32 v75, a51
	v_accvgpr_read_b32 v69, a33
	v_accvgpr_read_b32 v70, a34
	v_accvgpr_read_b32 v71, a35
	v_accvgpr_read_b32 v77, a21
	v_accvgpr_read_b32 v78, a22
	v_accvgpr_read_b32 v79, a23
	v_sub_f32_e32 v113, v246, v112
	v_exp_f32_e32 v114, v113
	s_nop 0
	v_pk_mul_f32 v[76:77], v[76:77], v[114:115] op_sel_hi:[1,0]
	v_pk_mul_f32 v[68:69], v[68:69], v[114:115] op_sel_hi:[1,0]
	v_pk_mul_f32 v[72:73], v[72:73], v[114:115] op_sel_hi:[1,0]
	v_pk_mul_f32 v[64:65], v[64:65], v[114:115] op_sel_hi:[1,0]
	v_pk_mul_f32 v[62:63], v[62:63], v[114:115] op_sel_hi:[1,0]
	v_pk_mul_f32 v[58:59], v[58:59], v[114:115] op_sel_hi:[1,0]
	v_pk_mul_f32 v[54:55], v[54:55], v[114:115] op_sel_hi:[1,0]
	v_pk_mul_f32 v[50:51], v[50:51], v[114:115] op_sel_hi:[1,0]
	v_pk_mul_f32 v[78:79], v[78:79], v[114:115] op_sel_hi:[1,0]
	v_pk_mul_f32 v[70:71], v[70:71], v[114:115] op_sel_hi:[1,0]
	v_pk_mul_f32 v[74:75], v[74:75], v[114:115] op_sel_hi:[1,0]
	v_pk_mul_f32 v[66:67], v[66:67], v[114:115] op_sel_hi:[1,0]
	v_pk_mul_f32 v[60:61], v[60:61], v[114:115] op_sel_hi:[1,0]
	v_pk_mul_f32 v[56:57], v[56:57], v[114:115] op_sel_hi:[1,0]
	v_pk_mul_f32 v[52:53], v[52:53], v[114:115] op_sel_hi:[1,0]
	v_pk_mul_f32 v[48:49], v[48:49], v[114:115] op_sel_hi:[1,0]
	v_accvgpr_write_b32 a115, v55
	v_accvgpr_write_b32 a127, v51
	v_accvgpr_write_b32 a99, v59
	v_accvgpr_write_b32 a83, v63
	v_accvgpr_write_b32 a60, v64
	v_accvgpr_write_b32 a48, v72
	v_accvgpr_write_b32 a32, v68
	v_accvgpr_write_b32 a20, v76
	v_mul_f32_e32 v233, v233, v114
	v_accvgpr_write_b32 a126, v50
	v_accvgpr_write_b32 a125, v49
	v_accvgpr_write_b32 a124, v48
	v_accvgpr_write_b32 a114, v54
	v_accvgpr_write_b32 a113, v53
	v_accvgpr_write_b32 a112, v52
	v_accvgpr_write_b32 a98, v58
	v_accvgpr_write_b32 a97, v57
	v_accvgpr_write_b32 a96, v56
	v_accvgpr_write_b32 a82, v62
	v_accvgpr_write_b32 a81, v61
	v_accvgpr_write_b32 a80, v60
	v_accvgpr_write_b32 a61, v65
	v_accvgpr_write_b32 a62, v66
	v_accvgpr_write_b32 a63, v67
	v_accvgpr_write_b32 a49, v73
	v_accvgpr_write_b32 a50, v74
	v_accvgpr_write_b32 a51, v75
	v_accvgpr_write_b32 a33, v69
	v_accvgpr_write_b32 a34, v70
	v_accvgpr_write_b32 a35, v71
	v_accvgpr_write_b32 a21, v77
	v_accvgpr_write_b32 a22, v78
	v_accvgpr_write_b32 a23, v79
	s_branch .LBB0_1976
; DI float max3_(float a, float b, float c) { float r; asm("v_max3_f32 %0, %1, %2, %3" : "=v"(r) : "v"(a), "v"(b), "v"(c)); return r; }
; template <int DQK, bool BIAS>
; __device__ __forceinline__ void attn_pass(const hf* __restrict__ Q, int ldq, const hf* __restrict__ Kp, int ldk, const hf* __restrict__ VT,
;                                           int s0, int L, int q0, float scale_l2, const float* sBias, f4 (&oacc)[8][4], char* smem) {
;     ...
;       if (BIAS) {
;         if (uni) {
; #pragma unroll
;           for (int mk = 0; mk < 4; ++mk)
; #pragma unroll
;             for (int j = 0; j < 4; ++j) sacc[mk][nq][j] = sacc[mk][nq][j] * scale_l2 + add;
;         } else {
; #pragma unroll
;           for (int mk = 0; mk < 4; ++mk)
; #pragma unroll
;             for (int j = 0; j < 4; ++j) {
;               int rel = (key0 + mk * 16 + fq * 4 + j) - (q0 + wv * 64 + nq * 16 + fr);
;               rel = min(max(rel, -128), 128);
;               sacc[mk][nq][j] = sacc[mk][nq][j] * scale_l2 + sBias[rel + 128];
;             }
;         }
;       }
;       float mx = -1e30f;
; #pragma unroll
;       for (int mk = 0; mk < 4; ++mk) { mx = max3_(mx, sacc[mk][nq][0], sacc[mk][nq][1]); mx = max3_(mx, sacc[mk][nq][2], sacc[mk][nq][3]); }
;       mx = max3_(mx, shx(mx, 16), mx); mx = max3_(mx, shx(mx, 32), mx);
;       if (!BIAS) mx *= scale_l2;
;       const bool upd = mx > mrun[nq] + 8.f;
;       const float mnew = upd ? mx : mrun[nq];
.Lattn_fast:
	s_waitcnt lgkmcnt(0)
	v_pk_fma_f32 v[34:35], v[190:191], s[22:23], v[196:197] op_sel_hi:[1,0,0]
	v_pk_fma_f32 v[82:83], v[174:175], s[22:23], v[196:197] op_sel_hi:[1,0,0]
	v_pk_fma_f32 v[130:131], v[158:159], s[22:23], v[196:197] op_sel_hi:[1,0,0]
	v_pk_fma_f32 v[98:99], v[126:127], s[22:23], v[196:197] op_sel_hi:[1,0,0]
	v_pk_fma_f32 v[32:33], v[188:189], s[22:23], v[196:197] op_sel_hi:[1,0,0]
	v_pk_fma_f32 v[80:81], v[172:173], s[22:23], v[196:197] op_sel_hi:[1,0,0]
	v_pk_fma_f32 v[128:129], v[156:157], s[22:23], v[196:197] op_sel_hi:[1,0,0]
	v_pk_fma_f32 v[96:97], v[124:125], s[22:23], v[196:197] op_sel_hi:[1,0,0]
	v_pk_fma_f32 v[46:47], v[186:187], s[22:23], v[196:197] op_sel_hi:[1,0,0]
	v_pk_fma_f32 v[94:95], v[170:171], s[22:23], v[196:197] op_sel_hi:[1,0,0]
	v_pk_fma_f32 v[142:143], v[154:155], s[22:23], v[196:197] op_sel_hi:[1,0,0]
	v_pk_fma_f32 v[106:107], v[122:123], s[22:23], v[196:197] op_sel_hi:[1,0,0]
	v_pk_fma_f32 v[44:45], v[184:185], s[22:23], v[196:197] op_sel_hi:[1,0,0]
	v_pk_fma_f32 v[92:93], v[168:169], s[22:23], v[196:197] op_sel_hi:[1,0,0]
	v_pk_fma_f32 v[140:141], v[152:153], s[22:23], v[196:197] op_sel_hi:[1,0,0]
	v_pk_fma_f32 v[104:105], v[120:121], s[22:23], v[196:197] op_sel_hi:[1,0,0]
	v_pk_fma_f32 v[42:43], v[182:183], s[22:23], v[196:197] op_sel_hi:[1,0,0]
	v_pk_fma_f32 v[86:87], v[166:167], s[22:23], v[196:197] op_sel_hi:[1,0,0]
	v_pk_fma_f32 v[138:139], v[150:151], s[22:23], v[196:197] op_sel_hi:[1,0,0]
	v_pk_fma_f32 v[102:103], v[118:119], s[22:23], v[196:197] op_sel_hi:[1,0,0]
	v_pk_fma_f32 v[40:41], v[180:181], s[22:23], v[196:197] op_sel_hi:[1,0,0]
	v_pk_fma_f32 v[84:85], v[164:165], s[22:23], v[196:197] op_sel_hi:[1,0,0]
	v_pk_fma_f32 v[136:137], v[148:149], s[22:23], v[196:197] op_sel_hi:[1,0,0]
	v_pk_fma_f32 v[100:101], v[116:117], s[22:23], v[196:197] op_sel_hi:[1,0,0]
	v_pk_fma_f32 v[38:39], v[178:179], s[22:23], v[196:197] op_sel_hi:[1,0,0]
	v_pk_fma_f32 v[90:91], v[162:163], s[22:23], v[196:197] op_sel_hi:[1,0,0]
	v_pk_fma_f32 v[134:135], v[146:147], s[22:23], v[196:197] op_sel_hi:[1,0,0]
	v_pk_fma_f32 v[110:111], v[114:115], s[22:23], v[196:197] op_sel_hi:[1,0,0]
	v_pk_fma_f32 v[36:37], v[176:177], s[22:23], v[196:197] op_sel_hi:[1,0,0]
	v_pk_fma_f32 v[88:89], v[160:161], s[22:23], v[196:197] op_sel_hi:[1,0,0]
	v_pk_fma_f32 v[132:133], v[144:145], s[22:23], v[196:197] op_sel_hi:[1,0,0]
	v_pk_fma_f32 v[108:109], v[112:113], s[22:23], v[196:197] op_sel_hi:[1,0,0]
	v_max3_f32 v176, v199, v32, v33
	v_max3_f32 v160, v199, v80, v81
	v_max3_f32 v144, v199, v128, v129
	v_max3_f32 v112, v199, v96, v97
	v_max3_f32 v176, v176, v34, v35
	v_max3_f32 v160, v160, v82, v83
	v_max3_f32 v144, v144, v130, v131
	v_max3_f32 v112, v112, v98, v99
	v_max3_f32 v176, v176, v44, v45
	v_max3_f32 v160, v160, v92, v93
	v_max3_f32 v144, v144, v140, v141
	v_max3_f32 v112, v112, v104, v105
	v_max3_f32 v176, v176, v46, v47
	v_max3_f32 v160, v160, v94, v95
	v_max3_f32 v144, v144, v142, v143
	v_max3_f32 v112, v112, v106, v107
	v_max3_f32 v176, v176, v40, v41
	v_max3_f32 v160, v160, v84, v85
	v_max3_f32 v144, v144, v136, v137
	v_max3_f32 v112, v112, v100, v101
	v_max3_f32 v176, v176, v42, v43
	v_max3_f32 v160, v160, v86, v87
	v_max3_f32 v144, v144, v138, v139
	v_max3_f32 v112, v112, v102, v103
	v_max3_f32 v176, v176, v36, v37
	v_max3_f32 v160, v160, v88, v89
	v_max3_f32 v144, v144, v132, v133
	v_max3_f32 v112, v112, v108, v109
	v_max3_f32 v176, v176, v38, v39
	v_max3_f32 v160, v160, v90, v91
	v_max3_f32 v144, v144, v134, v135
	v_max3_f32 v112, v112, v110, v111
	v_mov_b32_e32 v177, v176
	v_mov_b32_e32 v161, v160
	v_mov_b32_e32 v145, v144
	v_mov_b32_e32 v113, v112
	v_permlane16_swap_b32_e32 v177, v176
	v_permlane16_swap_b32_e32 v161, v160
	v_permlane16_swap_b32_e32 v145, v144
	v_permlane16_swap_b32_e32 v113, v112
	v_max_f32_e32 v176, v176, v177
	v_max_f32_e32 v160, v160, v161
	v_max_f32_e32 v144, v144, v145
	v_max_f32_e32 v112, v112, v113
	v_mov_b32_e32 v177, v176
	v_mov_b32_e32 v161, v160
	v_mov_b32_e32 v145, v144
	v_mov_b32_e32 v113, v112
	v_permlane32_swap_b32_e32 v177, v176
	v_permlane32_swap_b32_e32 v161, v160
	v_permlane32_swap_b32_e32 v145, v144
	v_permlane32_swap_b32_e32 v113, v112
	v_max_f32_e32 v176, v176, v177
	v_max_f32_e32 v160, v160, v161
	v_max_f32_e32 v144, v144, v145
	v_max_f32_e32 v112, v112, v113
	v_add_f32_e32 v177, 0x41000000, v198
	v_add_f32_e32 v161, 0x41000000, v253
	v_add_f32_e32 v145, 0x41000000, v247
	v_add_f32_e32 v113, 0x41000000, v246
	v_cmp_gt_f32_e64 s[16:17], v176, v177
	v_cmp_gt_f32_e64 s[26:27], v160, v161
	v_cmp_gt_f32_e64 s[70:71], v144, v145
	v_cmp_gt_f32_e32 vcc, v112, v113
	v_cndmask_b32_e64 v176, v198, v176, s[16:17]
	v_cndmask_b32_e64 v160, v253, v160, s[26:27]
	v_cndmask_b32_e64 v144, v247, v144, s[70:71]
	v_cndmask_b32_e32 v112, v246, v112, vcc
	s_nop 1
	s_or_b64 s[16:17], s[16:17], s[26:27]
	s_or_b64 s[70:71], s[70:71], vcc
	s_or_b64 s[16:17], s[16:17], s[70:71]
	s_cbranch_scc1 .Lattn_slow

; template <int DQK, bool BIAS>
; __device__ __forceinline__ void attn_pass(const hf* __restrict__ Q, int ldq, const hf* __restrict__ Kp, int ldk, const hf* __restrict__ VT,
;                                           int s0, int L, int q0, float scale_l2, const float* sBias, f4 (&oacc)[8][4], char* smem) {
;     ...
;       const bool upd = mx > mrun[nq] + 8.f;
;       const float mnew = upd ? mx : mrun[nq];
;       if (__builtin_amdgcn_ballot_w64(upd) != 0) {
;         const float alpha = __builtin_amdgcn_exp2f(mrun[nq] - mnew);
;         lrun[nq] *= alpha;
; #pragma unroll
;         for (int md = 0; md < 8; ++md) { oacc[md][nq][0] *= alpha; oacc[md][nq][1] *= alpha; oacc[md][nq][2] *= alpha; oacc[md][nq][3] *= alpha; }
;       }
.Lattn_slow:
	v_cmp_lg_f32_e32 vcc, v176, v198
	s_nop 3
	s_cbranch_vccz .Lattn_slow_1
	v_accvgpr_read_b32 v55, a95
	v_accvgpr_read_b32 v51, a107
	v_accvgpr_read_b32 v56, a76
	v_accvgpr_read_b32 v60, a64
	v_accvgpr_read_b32 v64, a44
	v_accvgpr_read_b32 v72, a24
	v_accvgpr_read_b32 v68, a8
	v_accvgpr_read_b32 v76, a0
	v_accvgpr_read_b32 v50, a106
	v_accvgpr_read_b32 v49, a105
	v_accvgpr_read_b32 v48, a104
	v_accvgpr_read_b32 v54, a94
	v_accvgpr_read_b32 v53, a93
	v_accvgpr_read_b32 v52, a92
	v_accvgpr_read_b32 v57, a77
	v_accvgpr_read_b32 v58, a78
	v_accvgpr_read_b32 v59, a79
	v_accvgpr_read_b32 v61, a65
	v_accvgpr_read_b32 v62, a66
	v_accvgpr_read_b32 v63, a67
	v_accvgpr_read_b32 v65, a45
	v_accvgpr_read_b32 v66, a46
	v_accvgpr_read_b32 v67, a47
	v_accvgpr_read_b32 v73, a25
	v_accvgpr_read_b32 v74, a26
	v_accvgpr_read_b32 v75, a27
	v_accvgpr_read_b32 v69, a9
	v_accvgpr_read_b32 v70, a10
	v_accvgpr_read_b32 v71, a11
	v_accvgpr_read_b32 v77, a1
	v_accvgpr_read_b32 v78, a2
	v_accvgpr_read_b32 v79, a3
	v_sub_f32_e32 v177, v198, v176
	v_exp_f32_e32 v178, v177
	s_nop 0
	v_pk_mul_f32 v[76:77], v[76:77], v[178:179] op_sel_hi:[1,0]
	v_pk_mul_f32 v[68:69], v[68:69], v[178:179] op_sel_hi:[1,0]
	v_pk_mul_f32 v[72:73], v[72:73], v[178:179] op_sel_hi:[1,0]
	v_pk_mul_f32 v[64:65], v[64:65], v[178:179] op_sel_hi:[1,0]
	v_pk_mul_f32 v[60:61], v[60:61], v[178:179] op_sel_hi:[1,0]
	v_pk_mul_f32 v[56:57], v[56:57], v[178:179] op_sel_hi:[1,0]
	v_pk_mul_f32 v[54:55], v[54:55], v[178:179] op_sel_hi:[1,0]
	v_pk_mul_f32 v[50:51], v[50:51], v[178:179] op_sel_hi:[1,0]
	v_pk_mul_f32 v[78:79], v[78:79], v[178:179] op_sel_hi:[1,0]
	v_pk_mul_f32 v[70:71], v[70:71], v[178:179] op_sel_hi:[1,0]
	v_pk_mul_f32 v[74:75], v[74:75], v[178:179] op_sel_hi:[1,0]
	v_pk_mul_f32 v[66:67], v[66:67], v[178:179] op_sel_hi:[1,0]
	v_pk_mul_f32 v[62:63], v[62:63], v[178:179] op_sel_hi:[1,0]
	v_pk_mul_f32 v[58:59], v[58:59], v[178:179] op_sel_hi:[1,0]
	v_pk_mul_f32 v[52:53], v[52:53], v[178:179] op_sel_hi:[1,0]
	v_pk_mul_f32 v[48:49], v[48:49], v[178:179] op_sel_hi:[1,0]
	v_accvgpr_write_b32 a95, v55
	v_accvgpr_write_b32 a107, v51
	v_accvgpr_write_b32 a76, v56
	v_accvgpr_write_b32 a64, v60
	v_accvgpr_write_b32 a44, v64
	v_accvgpr_write_b32 a24, v72
	v_accvgpr_write_b32 a8, v68
	v_accvgpr_write_b32 a0, v76
	v_mul_f32_e32 v245, v245, v178
	v_accvgpr_write_b32 a106, v50
	v_accvgpr_write_b32 a105, v49
	v_accvgpr_write_b32 a104, v48
	v_accvgpr_write_b32 a94, v54
	v_accvgpr_write_b32 a93, v53
	v_accvgpr_write_b32 a92, v52
	v_accvgpr_write_b32 a77, v57
	v_accvgpr_write_b32 a78, v58
	v_accvgpr_write_b32 a79, v59
	v_accvgpr_write_b32 a65, v61
	v_accvgpr_write_b32 a66, v62
	v_accvgpr_write_b32 a67, v63
	v_accvgpr_write_b32 a45, v65
	v_accvgpr_write_b32 a46, v66
	v_accvgpr_write_b32 a47, v67
	v_accvgpr_write_b32 a25, v73
	v_accvgpr_write_b32 a26, v74
	v_accvgpr_write_b32 a27, v75
	v_accvgpr_write_b32 a9, v69
	v_accvgpr_write_b32 a10, v70
	v_accvgpr_write_b32 a11, v71
	v_accvgpr_write_b32 a1, v77
	v_accvgpr_write_b32 a2, v78
	v_accvgpr_write_b32 a3, v79
.Lattn_slow_1:
	v_cmp_lg_f32_e32 vcc, v160, v253
	s_nop 3
	s_cbranch_vccz .Lattn_slow_2
	v_accvgpr_read_b32 v52, a100
	v_accvgpr_read_b32 v48, a116
	v_accvgpr_read_b32 v56, a84
	v_accvgpr_read_b32 v60, a68
	v_accvgpr_read_b32 v64, a52
	v_accvgpr_read_b32 v72, a36
	v_accvgpr_read_b32 v68, a16
	v_accvgpr_read_b32 v76, a4
	v_accvgpr_read_b32 v49, a117
	v_accvgpr_read_b32 v50, a118
	v_accvgpr_read_b32 v51, a119
	v_accvgpr_read_b32 v53, a101
	v_accvgpr_read_b32 v54, a102
	v_accvgpr_read_b32 v55, a103
	v_accvgpr_read_b32 v57, a85
	v_accvgpr_read_b32 v58, a86
	v_accvgpr_read_b32 v59, a87
	v_accvgpr_read_b32 v61, a69
	v_accvgpr_read_b32 v62, a70
	v_accvgpr_read_b32 v63, a71
	v_accvgpr_read_b32 v65, a53
	v_accvgpr_read_b32 v66, a54
	v_accvgpr_read_b32 v67, a55
	v_accvgpr_read_b32 v73, a37
	v_accvgpr_read_b32 v74, a38
	v_accvgpr_read_b32 v75, a39
	v_accvgpr_read_b32 v69, a17
	v_accvgpr_read_b32 v70, a18
	v_accvgpr_read_b32 v71, a19
	v_accvgpr_read_b32 v77, a5
	v_accvgpr_read_b32 v78, a6
	v_accvgpr_read_b32 v79, a7
	v_sub_f32_e32 v161, v253, v160
	v_exp_f32_e32 v162, v161
	s_nop 0
	v_pk_mul_f32 v[76:77], v[76:77], v[162:163] op_sel_hi:[1,0]
	v_pk_mul_f32 v[68:69], v[68:69], v[162:163] op_sel_hi:[1,0]
	v_pk_mul_f32 v[72:73], v[72:73], v[162:163] op_sel_hi:[1,0]
	v_pk_mul_f32 v[64:65], v[64:65], v[162:163] op_sel_hi:[1,0]
	v_pk_mul_f32 v[60:61], v[60:61], v[162:163] op_sel_hi:[1,0]
	v_pk_mul_f32 v[56:57], v[56:57], v[162:163] op_sel_hi:[1,0]
	v_pk_mul_f32 v[52:53], v[52:53], v[162:163] op_sel_hi:[1,0]
	v_pk_mul_f32 v[48:49], v[48:49], v[162:163] op_sel_hi:[1,0]
	v_pk_mul_f32 v[78:79], v[78:79], v[162:163] op_sel_hi:[1,0]
	v_pk_mul_f32 v[70:71], v[70:71], v[162:163] op_sel_hi:[1,0]
	v_pk_mul_f32 v[74:75], v[74:75], v[162:163] op_sel_hi:[1,0]
	v_pk_mul_f32 v[66:67], v[66:67], v[162:163] op_sel_hi:[1,0]
	v_pk_mul_f32 v[62:63], v[62:63], v[162:163] op_sel_hi:[1,0]
	v_pk_mul_f32 v[58:59], v[58:59], v[162:163] op_sel_hi:[1,0]
	v_pk_mul_f32 v[54:55], v[54:55], v[162:163] op_sel_hi:[1,0]
	v_pk_mul_f32 v[50:51], v[50:51], v[162:163] op_sel_hi:[1,0]
	v_accvgpr_write_b32 a100, v52
	v_accvgpr_write_b32 a116, v48
	v_accvgpr_write_b32 a84, v56
	v_accvgpr_write_b32 a68, v60
	v_accvgpr_write_b32 a52, v64
	v_accvgpr_write_b32 a36, v72
	v_accvgpr_write_b32 a16, v68
	v_accvgpr_write_b32 a4, v76
	v_mul_f32_e32 v243, v243, v162
	v_accvgpr_write_b32 a117, v49
	v_accvgpr_write_b32 a118, v50
	v_accvgpr_write_b32 a119, v51
	v_accvgpr_write_b32 a101, v53
	v_accvgpr_write_b32 a102, v54
	v_accvgpr_write_b32 a103, v55
	v_accvgpr_write_b32 a85, v57
	v_accvgpr_write_b32 a86, v58
	v_accvgpr_write_b32 a87, v59
	v_accvgpr_write_b32 a69, v61
	v_accvgpr_write_b32 a70, v62
	v_accvgpr_write_b32 a71, v63
	v_accvgpr_write_b32 a53, v65
	v_accvgpr_write_b32 a54, v66
	v_accvgpr_write_b32 a55, v67
	v_accvgpr_write_b32 a37, v73
	v_accvgpr_write_b32 a38, v74
	v_accvgpr_write_b32 a39, v75
	v_accvgpr_write_b32 a17, v69
	v_accvgpr_write_b32 a18, v70
	v_accvgpr_write_b32 a19, v71
	v_accvgpr_write_b32 a5, v77
	v_accvgpr_write_b32 a6, v78
	v_accvgpr_write_b32 a7, v79
; template <int DQK, bool BIAS>
; __device__ __forceinline__ void attn_pass(const hf* __restrict__ Q, int ldq, const hf* __restrict__ Kp, int ldk, const hf* __restrict__ VT,
;                                           int s0, int L, int q0, float scale_l2, const float* sBias, f4 (&oacc)[8][4], char* smem) {
;     ...
;       const bool upd = mx > mrun[nq] + 8.f;
;       const float mnew = upd ? mx : mrun[nq];
;       if (__builtin_amdgcn_ballot_w64(upd) != 0) {
;         const float alpha = __builtin_amdgcn_exp2f(mrun[nq] - mnew);
;         lrun[nq] *= alpha;
; #pragma unroll
;         for (int md = 0; md < 8; ++md) { oacc[md][nq][0] *= alpha; oacc[md][nq][1] *= alpha; oacc[md][nq][2] *= alpha; oacc[md][nq][3] *= alpha; }
;       }
.Lattn_slow_2:
	v_cmp_lg_f32_e32 vcc, v144, v247
	s_nop 3
	s_cbranch_vccz .Lattn_slow_3
	v_accvgpr_read_b32 v55, a111
	v_accvgpr_read_b32 v51, a123
	v_accvgpr_read_b32 v56, a88
	v_accvgpr_read_b32 v60, a72
	v_accvgpr_read_b32 v64, a56
	v_accvgpr_read_b32 v72, a40
	v_accvgpr_read_b32 v68, a28
	v_accvgpr_read_b32 v76, a12
	v_accvgpr_read_b32 v50, a122
	v_accvgpr_read_b32 v49, a121
	v_accvgpr_read_b32 v48, a120
	v_accvgpr_read_b32 v54, a110
	v_accvgpr_read_b32 v53, a109
	v_accvgpr_read_b32 v52, a108
	v_accvgpr_read_b32 v57, a89
	v_accvgpr_read_b32 v58, a90
	v_accvgpr_read_b32 v59, a91
	v_accvgpr_read_b32 v61, a73
	v_accvgpr_read_b32 v62, a74
	v_accvgpr_read_b32 v63, a75
	v_accvgpr_read_b32 v65, a57
	v_accvgpr_read_b32 v66, a58
	v_accvgpr_read_b32 v67, a59
	v_accvgpr_read_b32 v73, a41
	v_accvgpr_read_b32 v74, a42
	v_accvgpr_read_b32 v75, a43
	v_accvgpr_read_b32 v69, a29
	v_accvgpr_read_b32 v70, a30
	v_accvgpr_read_b32 v71, a31
	v_accvgpr_read_b32 v77, a13
	v_accvgpr_read_b32 v78, a14
	v_accvgpr_read_b32 v79, a15
	v_sub_f32_e32 v145, v247, v144
	v_exp_f32_e32 v146, v145
	s_nop 0
	v_pk_mul_f32 v[76:77], v[76:77], v[146:147] op_sel_hi:[1,0]
	v_pk_mul_f32 v[68:69], v[68:69], v[146:147] op_sel_hi:[1,0]
	v_pk_mul_f32 v[72:73], v[72:73], v[146:147] op_sel_hi:[1,0]
	v_pk_mul_f32 v[64:65], v[64:65], v[146:147] op_sel_hi:[1,0]
	v_pk_mul_f32 v[60:61], v[60:61], v[146:147] op_sel_hi:[1,0]
	v_pk_mul_f32 v[56:57], v[56:57], v[146:147] op_sel_hi:[1,0]
	v_pk_mul_f32 v[54:55], v[54:55], v[146:147] op_sel_hi:[1,0]
	v_pk_mul_f32 v[50:51], v[50:51], v[146:147] op_sel_hi:[1,0]
	v_pk_mul_f32 v[78:79], v[78:79], v[146:147] op_sel_hi:[1,0]
	v_pk_mul_f32 v[70:71], v[70:71], v[146:147] op_sel_hi:[1,0]
	v_pk_mul_f32 v[74:75], v[74:75], v[146:147] op_sel_hi:[1,0]
	v_pk_mul_f32 v[66:67], v[66:67], v[146:147] op_sel_hi:[1,0]
	v_pk_mul_f32 v[62:63], v[62:63], v[146:147] op_sel_hi:[1,0]
	v_pk_mul_f32 v[58:59], v[58:59], v[146:147] op_sel_hi:[1,0]
	v_pk_mul_f32 v[52:53], v[52:53], v[146:147] op_sel_hi:[1,0]
	v_pk_mul_f32 v[48:49], v[48:49], v[146:147] op_sel_hi:[1,0]
	v_accvgpr_write_b32 a111, v55
	v_accvgpr_write_b32 a123, v51
	v_accvgpr_write_b32 a88, v56
	v_accvgpr_write_b32 a72, v60
	v_accvgpr_write_b32 a56, v64
	v_accvgpr_write_b32 a40, v72
	v_accvgpr_write_b32 a28, v68
	v_accvgpr_write_b32 a12, v76
	v_mul_f32_e32 v242, v242, v146
	v_accvgpr_write_b32 a122, v50
	v_accvgpr_write_b32 a121, v49
	v_accvgpr_write_b32 a120, v48
	v_accvgpr_write_b32 a110, v54
	v_accvgpr_write_b32 a109, v53
	v_accvgpr_write_b32 a108, v52
	v_accvgpr_write_b32 a89, v57
	v_accvgpr_write_b32 a90, v58
	v_accvgpr_write_b32 a91, v59
	v_accvgpr_write_b32 a73, v61
	v_accvgpr_write_b32 a74, v62
	v_accvgpr_write_b32 a75, v63
	v_accvgpr_write_b32 a57, v65
	v_accvgpr_write_b32 a58, v66
	v_accvgpr_write_b32 a59, v67
	v_accvgpr_write_b32 a41, v73
	v_accvgpr_write_b32 a42, v74
	v_accvgpr_write_b32 a43, v75
	v_accvgpr_write_b32 a29, v69
	v_accvgpr_write_b32 a30, v70
	v_accvgpr_write_b32 a31, v71
	v_accvgpr_write_b32 a13, v77
	v_accvgpr_write_b32 a14, v78
	v_accvgpr_write_b32 a15, v79
.Lattn_slow_3:
	v_cmp_lg_f32_e32 vcc, v112, v246
	s_nop 3
	s_cbranch_vccz .Lattn_slow_4
	v_accvgpr_read_b32 v55, a115
	v_accvgpr_read_b32 v51, a127
	v_accvgpr_read_b32 v59, a99
	v_accvgpr_read_b32 v63, a83
	v_accvgpr_read_b32 v64, a60
	v_accvgpr_read_b32 v72, a48
	v_accvgpr_read_b32 v68, a32
	v_accvgpr_read_b32 v76, a20
	v_accvgpr_read_b32 v50, a126
	v_accvgpr_read_b32 v49, a125
	v_accvgpr_read_b32 v48, a124
	v_accvgpr_read_b32 v54, a114
	v_accvgpr_read_b32 v53, a113
	v_accvgpr_read_b32 v52, a112
	v_accvgpr_read_b32 v58, a98
	v_accvgpr_read_b32 v57, a97
	v_accvgpr_read_b32 v56, a96
	v_accvgpr_read_b32 v62, a82
	v_accvgpr_read_b32 v61, a81
	v_accvgpr_read_b32 v60, a80
	v_accvgpr_read_b32 v65, a61
	v_accvgpr_read_b32 v66, a62
	v_accvgpr_read_b32 v67, a63
	v_accvgpr_read_b32 v73, a49
	v_accvgpr_read_b32 v74, a50
	v_accvgpr_read_b32 v75, a51
	v_accvgpr_read_b32 v69, a33
	v_accvgpr_read_b32 v70, a34
	v_accvgpr_read_b32 v71, a35
	v_accvgpr_read_b32 v77, a21
	v_accvgpr_read_b32 v78, a22
	v_accvgpr_read_b32 v79, a23
	v_sub_f32_e32 v113, v246, v112
	v_exp_f32_e32 v114, v113
	s_nop 0
	v_pk_mul_f32 v[76:77], v[76:77], v[114:115] op_sel_hi:[1,0]
	v_pk_mul_f32 v[68:69], v[68:69], v[114:115] op_sel_hi:[1,0]
	v_pk_mul_f32 v[72:73], v[72:73], v[114:115] op_sel_hi:[1,0]
	v_pk_mul_f32 v[64:65], v[64:65], v[114:115] op_sel_hi:[1,0]
	v_pk_mul_f32 v[62:63], v[62:63], v[114:115] op_sel_hi:[1,0]
	v_pk_mul_f32 v[58:59], v[58:59], v[114:115] op_sel_hi:[1,0]
	v_pk_mul_f32 v[54:55], v[54:55], v[114:115] op_sel_hi:[1,0]
	v_pk_mul_f32 v[50:51], v[50:51], v[114:115] op_sel_hi:[1,0]
	v_pk_mul_f32 v[78:79], v[78:79], v[114:115] op_sel_hi:[1,0]
	v_pk_mul_f32 v[70:71], v[70:71], v[114:115] op_sel_hi:[1,0]
	v_pk_mul_f32 v[74:75], v[74:75], v[114:115] op_sel_hi:[1,0]
	v_pk_mul_f32 v[66:67], v[66:67], v[114:115] op_sel_hi:[1,0]
	v_pk_mul_f32 v[60:61], v[60:61], v[114:115] op_sel_hi:[1,0]
	v_pk_mul_f32 v[56:57], v[56:57], v[114:115] op_sel_hi:[1,0]
	v_pk_mul_f32 v[52:53], v[52:53], v[114:115] op_sel_hi:[1,0]
	v_pk_mul_f32 v[48:49], v[48:49], v[114:115] op_sel_hi:[1,0]
	v_accvgpr_write_b32 a115, v55
	v_accvgpr_write_b32 a127, v51
	v_accvgpr_write_b32 a99, v59
	v_accvgpr_write_b32 a83, v63
	v_accvgpr_write_b32 a60, v64
	v_accvgpr_write_b32 a48, v72
	v_accvgpr_write_b32 a32, v68
	v_accvgpr_write_b32 a20, v76
	v_mul_f32_e32 v233, v233, v114
	v_accvgpr_write_b32 a126, v50
	v_accvgpr_write_b32 a125, v49
	v_accvgpr_write_b32 a124, v48
	v_accvgpr_write_b32 a114, v54
	v_accvgpr_write_b32 a113, v53
	v_accvgpr_write_b32 a112, v52
	v_accvgpr_write_b32 a98, v58
	v_accvgpr_write_b32 a97, v57
	v_accvgpr_write_b32 a96, v56
	v_accvgpr_write_b32 a82, v62
	v_accvgpr_write_b32 a81, v61
	v_accvgpr_write_b32 a80, v60
	v_accvgpr_write_b32 a61, v65
	v_accvgpr_write_b32 a62, v66
	v_accvgpr_write_b32 a63, v67
	v_accvgpr_write_b32 a49, v73
	v_accvgpr_write_b32 a50, v74
	v_accvgpr_write_b32 a51, v75
	v_accvgpr_write_b32 a33, v69
	v_accvgpr_write_b32 a34, v70
	v_accvgpr_write_b32 a35, v71
	v_accvgpr_write_b32 a21, v77
	v_accvgpr_write_b32 a22, v78
	v_accvgpr_write_b32 a23, v79
; template <int DQK, bool BIAS>
; __device__ __forceinline__ void attn_pass(const hf* __restrict__ Q, int ldq, const hf* __restrict__ Kp, int ldk, const hf* __restrict__ VT,
;                                           int s0, int L, int q0, float scale_l2, const float* sBias, f4 (&oacc)[8][4], char* smem) {
;     ...
; #pragma unroll
;   for (int nq = 0; nq < 4; ++nq) {
;     float lt = lrun[nq]; lt += shx(lt, 16); lt += shx(lt, 32);
;     const float inv = 1.f / lt;
; #pragma unroll
;     for (int md = 0; md < 8; ++md) { oacc[md][nq][0] *= inv; oacc[md][nq][1] *= inv; oacc[md][nq][2] *= inv; oacc[md][nq][3] *= inv; }
;   }
.Lattn_slow_4:
	s_branch .LBB0_1976
.LBB0_1978:
	ds_swizzle_b32 v60, v245 offset:swizzle(SWAP,16)
	v_accvgpr_read_b32 v52, a64
	v_accvgpr_read_b32 v55, a67
	v_accvgpr_read_b32 v103, a3
	v_accvgpr_read_b32 v64, a104
	s_waitcnt lgkmcnt(0)
	v_add_f32_e32 v68, v245, v60
	v_mov_b32_e32 v60, v224
	v_accvgpr_read_b32 v89, a79
	v_lshlrev_b32_e32 v60, 2, v60
	v_bitop3_b32 v60, v60, s3, v226 bitop3:0x6c
	ds_bpermute_b32 v69, v60, v68
	v_accvgpr_read_b32 v63, a47
	v_accvgpr_read_b32 v85, a11
	v_accvgpr_read_b32 v102, a2
	v_accvgpr_read_b32 v101, a1
	s_waitcnt lgkmcnt(0)
	v_add_f32_e32 v76, v68, v69
	v_div_scale_f32 v77, s[16:17], v76, v76, 1.0
	v_rcp_f32_e32 v94, v77
	v_accvgpr_read_b32 v71, a27
	v_accvgpr_read_b32 v65, a105
	v_accvgpr_read_b32 v66, a106
	v_fma_f32 v95, -v77, v94, 1.0
	v_fmac_f32_e32 v94, v95, v94
	v_div_scale_f32 v95, vcc, 1.0, v76, 1.0
	v_mul_f32_e32 v108, v95, v94
	v_fma_f32 v109, -v77, v108, v95
	v_fmac_f32_e32 v108, v109, v94
	v_fma_f32 v77, -v77, v108, v95
	v_div_fmas_f32 v77, v77, v94, v108
	v_div_fixup_f32 v94, v77, v76, 1.0
	v_mul_f32_e32 v138, v55, v94
	ds_swizzle_b32 v55, v243 offset:swizzle(SWAP,16)
	v_mul_f32_e32 v141, v63, v94
	v_mov_b32_e32 v63, v224
	v_mul_f32_e32 v145, v71, v94
	v_lshlrev_b32_e32 v63, 2, v63
	s_waitcnt lgkmcnt(0)
	v_add_f32_e32 v55, v243, v55
	v_bitop3_b32 v63, v63, s3, v226 bitop3:0x6c
	ds_bpermute_b32 v63, v63, v55
	v_accvgpr_read_b32 v86, a76
	v_accvgpr_read_b32 v53, a65
	v_accvgpr_read_b32 v54, a66
	v_accvgpr_read_b32 v62, a46
	s_waitcnt lgkmcnt(0)
	v_add_f32_e32 v55, v55, v63
	v_div_scale_f32 v63, s[16:17], v55, v55, 1.0
	v_rcp_f32_e32 v71, v63
	v_accvgpr_read_b32 v61, a45
	v_accvgpr_read_b32 v60, a44
	v_accvgpr_read_b32 v70, a26
	v_accvgpr_read_b32 v69, a25
	v_accvgpr_read_b32 v68, a24
	v_accvgpr_read_b32 v84, a10
	v_accvgpr_read_b32 v83, a9
	v_mov_b32_e32 v76, v101
	v_mov_b32_e32 v77, v102
	v_accvgpr_read_b32 v88, a78
	v_accvgpr_read_b32 v100, a0
	v_pk_mul_f32 v[118:119], v[76:77], v[94:95] op_sel_hi:[1,0]
	v_mov_b32_e32 v76, v83
	v_mov_b32_e32 v77, v84
	v_mul_f32_e32 v84, v68, v94
	v_mov_b32_e32 v68, v69
	v_mov_b32_e32 v69, v70
	v_mul_f32_e32 v70, v60, v94
	v_mov_b32_e32 v60, v61
	v_mov_b32_e32 v61, v62
	v_mul_f32_e32 v62, v52, v94
	v_mov_b32_e32 v52, v53
	v_mov_b32_e32 v53, v54
	v_mul_f32_e32 v54, v86, v94
	v_mul_f32_e32 v86, v64, v94
	v_mov_b32_e32 v64, v65
	v_mov_b32_e32 v65, v66
	v_mul_f32_e32 v116, v100, v94
	v_pk_mul_f32 v[100:101], v[76:77], v[94:95] op_sel_hi:[1,0]
	v_pk_mul_f32 v[76:77], v[68:69], v[94:95] op_sel_hi:[1,0]
	v_pk_mul_f32 v[68:69], v[60:61], v[94:95] op_sel_hi:[1,0]
	v_pk_mul_f32 v[60:61], v[52:53], v[94:95] op_sel_hi:[1,0]
	v_mov_b32_e32 v53, v88
	v_mul_f32_e32 v152, v89, v94
	v_pk_mul_f32 v[88:89], v[64:65], v[94:95] op_sel_hi:[1,0]
	v_fma_f32 v64, -v63, v71, 1.0
	v_fmac_f32_e32 v71, v64, v71
	v_div_scale_f32 v64, vcc, 1.0, v55, 1.0
	v_mul_f32_e32 v65, v64, v71
	v_fma_f32 v66, -v63, v65, v64
	v_fmac_f32_e32 v65, v66, v71
	v_fma_f32 v63, -v63, v65, v64
	v_div_fmas_f32 v63, v63, v71, v65
	v_accvgpr_read_b32 v56, a68
	v_div_fixup_f32 v136, v63, v55, 1.0
	ds_swizzle_b32 v55, v242 offset:swizzle(SWAP,16)
	v_accvgpr_read_b32 v59, a71
	v_mul_f32_e32 v139, v59, v136
	v_mov_b32_e32 v59, v224
	s_waitcnt lgkmcnt(0)
	v_add_f32_e32 v55, v242, v55
	v_lshlrev_b32_e32 v59, 2, v59
	v_bitop3_b32 v59, v59, s3, v226 bitop3:0x6c
	ds_bpermute_b32 v59, v59, v55
	v_accvgpr_read_b32 v67, a107
	v_accvgpr_read_b32 v157, a7
	v_mul_f32_e32 v147, v67, v94
	v_accvgpr_read_b32 v72, a92
	s_waitcnt lgkmcnt(0)
	v_add_f32_e32 v55, v55, v59
	v_div_scale_f32 v59, s[16:17], v55, v55, 1.0
	v_rcp_f32_e32 v63, v59
	v_accvgpr_read_b32 v113, a19
	v_accvgpr_read_b32 v156, a6
	v_accvgpr_read_b32 v155, a5
	v_fma_f32 v67, -v59, v63, 1.0
	v_fmac_f32_e32 v63, v67, v63
	v_div_scale_f32 v67, vcc, 1.0, v55, 1.0
	v_accvgpr_read_b32 v75, a95
	v_accvgpr_read_b32 v93, a39
	v_accvgpr_read_b32 v112, a18
	v_accvgpr_read_b32 v111, a17
	v_mov_b32_e32 v64, v155
	v_mov_b32_e32 v65, v156
	v_mul_f32_e32 v71, v67, v63
	v_accvgpr_read_b32 v96, a100
	v_accvgpr_read_b32 v73, a93
	v_accvgpr_read_b32 v74, a94
	v_accvgpr_read_b32 v87, a77
	v_accvgpr_read_b32 v131, a55
	v_accvgpr_read_b32 v92, a38
	v_accvgpr_read_b32 v91, a37
	v_accvgpr_read_b32 v110, a16
	v_accvgpr_read_b32 v82, a8
	v_mul_f32_e32 v153, v75, v94
	v_pk_mul_f32 v[126:127], v[64:65], v[136:137] op_sel_hi:[1,0]
	v_mov_b32_e32 v64, v111
	v_mov_b32_e32 v65, v112
	v_fma_f32 v75, -v59, v71, v67
	v_accvgpr_read_b32 v78, a116
	v_accvgpr_read_b32 v97, a101
	v_accvgpr_read_b32 v98, a102
	v_accvgpr_read_b32 v107, a87
	v_accvgpr_read_b32 v57, a69
	v_accvgpr_read_b32 v58, a70
	v_accvgpr_read_b32 v130, a54
	v_accvgpr_read_b32 v129, a53
	v_accvgpr_read_b32 v90, a36
	v_mul_f32_e32 v108, v82, v94
	v_mov_b32_e32 v52, v87
	v_mul_f32_e32 v82, v72, v94
	v_mov_b32_e32 v72, v73
	v_mov_b32_e32 v73, v74
	v_mul_f32_e32 v114, v110, v136
	v_pk_mul_f32 v[110:111], v[64:65], v[136:137] op_sel_hi:[1,0]
	v_mov_b32_e32 v64, v91
	v_mov_b32_e32 v65, v92
	v_fmac_f32_e32 v71, v75, v63
	v_accvgpr_read_b32 v79, a117
	v_accvgpr_read_b32 v80, a118
	v_accvgpr_read_b32 v106, a86
	v_accvgpr_read_b32 v105, a85
	v_accvgpr_read_b32 v123, a15
	v_mul_f32_e32 v160, v103, v94
	v_mul_f32_e32 v151, v85, v94
	v_pk_mul_f32 v[52:53], v[52:53], v[94:95] op_sel_hi:[1,0]
	v_pk_mul_f32 v[102:103], v[72:73], v[94:95] op_sel_hi:[1,0]
	v_mul_f32_e32 v94, v90, v136
	v_pk_mul_f32 v[90:91], v[64:65], v[136:137] op_sel_hi:[1,0]
	v_mov_b32_e32 v64, v129
	v_mov_b32_e32 v65, v130
	v_mul_f32_e32 v66, v56, v136
	v_mov_b32_e32 v56, v57
	v_mov_b32_e32 v57, v58
	v_mul_f32_e32 v92, v96, v136
	v_mov_b32_e32 v96, v97
	v_mov_b32_e32 v97, v98
; template <int DQK, bool BIAS>
; __device__ __forceinline__ void attn_pass(const hf* __restrict__ Q, int ldq, const hf* __restrict__ Kp, int ldk, const hf* __restrict__ VT,
;                                           int s0, int L, int q0, float scale_l2, const float* sBias, f4 (&oacc)[8][4], char* smem) {
;     ...
; #pragma unroll
;   for (int nq = 0; nq < 4; ++nq) {
;     float lt = lrun[nq]; lt += shx(lt, 16); lt += shx(lt, 32);
;     const float inv = 1.f / lt;
; #pragma unroll
;     for (int md = 0; md < 8; ++md) { oacc[md][nq][0] *= inv; oacc[md][nq][1] *= inv; oacc[md][nq][2] *= inv; oacc[md][nq][3] *= inv; }
;   }
	v_fma_f32 v59, -v59, v71, v67
	v_accvgpr_read_b32 v81, a119
	v_accvgpr_read_b32 v99, a103
	v_accvgpr_read_b32 v104, a84
	v_accvgpr_read_b32 v171, a31
	v_accvgpr_read_b32 v122, a14
	v_accvgpr_read_b32 v121, a13
	v_accvgpr_read_b32 v128, a52
	v_accvgpr_read_b32 v154, a4
	v_mul_f32_e32 v156, v113, v136
	v_pk_mul_f32 v[72:73], v[64:65], v[136:137] op_sel_hi:[1,0]
	v_pk_mul_f32 v[64:65], v[56:57], v[136:137] op_sel_hi:[1,0]
	v_mov_b32_e32 v56, v105
	v_mov_b32_e32 v57, v106
	v_pk_mul_f32 v[112:113], v[96:97], v[136:137] op_sel_hi:[1,0]
	v_mul_f32_e32 v96, v78, v136
	v_mov_b32_e32 v78, v79
	v_mov_b32_e32 v79, v80
	v_div_fmas_f32 v59, v59, v63, v71
	v_accvgpr_read_b32 v44, a72
	v_accvgpr_read_b32 v48, a56
	v_accvgpr_read_b32 v135, a43
	v_accvgpr_read_b32 v170, a30
	v_accvgpr_read_b32 v169, a29
	v_mul_f32_e32 v124, v154, v136
	v_mul_f32_e32 v164, v157, v136
	v_mul_f32_e32 v148, v93, v136
	v_mul_f32_e32 v74, v128, v136
	v_mul_f32_e32 v143, v131, v136
	v_mul_f32_e32 v58, v104, v136
	v_pk_mul_f32 v[56:57], v[56:57], v[136:137] op_sel_hi:[1,0]
	v_mul_f32_e32 v157, v107, v136
	v_mul_f32_e32 v158, v99, v136
	v_pk_mul_f32 v[98:99], v[78:79], v[136:137] op_sel_hi:[1,0]
	v_mul_f32_e32 v150, v81, v136
	v_div_fixup_f32 v136, v59, v55, 1.0
	v_mov_b32_e32 v78, v121
	v_mov_b32_e32 v79, v122
	v_accvgpr_read_b32 v45, a73
	v_accvgpr_read_b32 v46, a74
	v_accvgpr_read_b32 v49, a57
	v_accvgpr_read_b32 v50, a58
	v_accvgpr_read_b32 v134, a42
	v_accvgpr_read_b32 v133, a41
	v_accvgpr_read_b32 v120, a12
	v_pk_mul_f32 v[130:131], v[78:79], v[136:137] op_sel_hi:[1,0]
	v_mov_b32_e32 v78, v169
	v_mov_b32_e32 v79, v170
	v_mul_f32_e32 v128, v120, v136
	v_pk_mul_f32 v[120:121], v[78:79], v[136:137] op_sel_hi:[1,0]
	v_mov_b32_e32 v78, v133
	v_mov_b32_e32 v79, v134
	v_mul_f32_e32 v80, v48, v136
	v_mov_b32_e32 v48, v49
	v_mov_b32_e32 v49, v50
	v_mul_f32_e32 v50, v44, v136
	v_mov_b32_e32 v44, v45
	v_mov_b32_e32 v45, v46
	v_accvgpr_read_b32 v36, a108
	v_accvgpr_read_b32 v40, a88
	v_pk_mul_f32 v[104:105], v[78:79], v[136:137] op_sel_hi:[1,0]
	v_pk_mul_f32 v[78:79], v[48:49], v[136:137] op_sel_hi:[1,0]
	v_pk_mul_f32 v[48:49], v[44:45], v[136:137] op_sel_hi:[1,0]
	ds_swizzle_b32 v45, v233 offset:swizzle(SWAP,16)
	v_accvgpr_read_b32 v38, a110
	v_accvgpr_read_b32 v43, a91
	v_mul_f32_e32 v162, v43, v136
	v_mov_b32_e32 v43, v38
	v_mov_b32_e32 v38, v224
	v_accvgpr_read_b32 v37, a109
	v_accvgpr_read_b32 v41, a89
	v_accvgpr_read_b32 v42, a90
	v_lshlrev_b32_e32 v38, 2, v38
	v_mul_f32_e32 v44, v40, v136
	v_mov_b32_e32 v40, v41
	v_mov_b32_e32 v41, v42
	v_mov_b32_e32 v42, v37
	s_waitcnt lgkmcnt(0)
	v_add_f32_e32 v37, v233, v45
	v_bitop3_b32 v38, v38, s3, v226 bitop3:0x6c
	ds_bpermute_b32 v45, v38, v37
	v_accvgpr_read_b32 v32, a120
	v_accvgpr_read_b32 v33, a121
	v_mov_b32_e32 v38, v33
	v_accvgpr_read_b32 v34, a122
	s_waitcnt lgkmcnt(0)
	v_add_f32_e32 v33, v37, v45
	v_div_scale_f32 v37, s[16:17], v33, v33, 1.0
	v_rcp_f32_e32 v45, v37
	v_accvgpr_read_b32 v39, a111
	v_mul_f32_e32 v163, v39, v136
	v_mov_b32_e32 v39, v34
	v_fma_f32 v34, -v37, v45, 1.0
	v_accvgpr_read_b32 v35, a123
	v_fmac_f32_e32 v45, v34, v45
	v_div_scale_f32 v34, vcc, 1.0, v33, 1.0
	v_mul_f32_e32 v155, v35, v136
	v_mul_f32_e32 v35, v34, v45
	v_fma_f32 v46, -v37, v35, v34
	v_fmac_f32_e32 v35, v46, v45
	v_fma_f32 v34, -v37, v35, v34
	v_accvgpr_read_b32 v8, a96
	v_accvgpr_read_b32 v12, a80
	v_accvgpr_read_b32 v16, a60
	v_accvgpr_read_b32 v20, a48
	v_accvgpr_read_b32 v24, a32
	v_accvgpr_read_b32 v31, a23
	v_accvgpr_read_b32 v132, a40
	v_div_fmas_f32 v34, v34, v45, v35
	v_accvgpr_read_b32 v4, a112
	v_accvgpr_read_b32 v9, a97
	v_accvgpr_read_b32 v10, a98
	v_accvgpr_read_b32 v13, a81
	v_accvgpr_read_b32 v14, a82
	v_accvgpr_read_b32 v17, a61
	v_accvgpr_read_b32 v18, a62
	v_accvgpr_read_b32 v21, a49
	v_accvgpr_read_b32 v22, a50
	v_accvgpr_read_b32 v25, a33
	v_accvgpr_read_b32 v26, a34
	v_accvgpr_read_b32 v30, a22
	v_accvgpr_read_b32 v29, a21
	v_accvgpr_read_b32 v28, a20
	v_mul_f32_e32 v106, v132, v136
	v_div_fixup_f32 v132, v34, v33, 1.0
	v_accvgpr_read_b32 v0, a124
	v_accvgpr_read_b32 v5, a113
	v_accvgpr_read_b32 v6, a114
	v_accvgpr_read_b32 v47, a75
	v_mul_f32_e32 v34, v28, v132
	v_mov_b32_e32 v28, v29
	v_mov_b32_e32 v29, v30
	v_mul_f32_e32 v30, v24, v132
	v_mov_b32_e32 v24, v25
	v_mov_b32_e32 v25, v26
	v_mul_f32_e32 v26, v20, v132
	v_mov_b32_e32 v20, v21
	v_mov_b32_e32 v21, v22
	v_mul_f32_e32 v22, v16, v132
	v_mov_b32_e32 v16, v17
	v_mov_b32_e32 v17, v18
	v_mul_f32_e32 v18, v12, v132
	v_mov_b32_e32 v12, v13
	v_mov_b32_e32 v13, v14
	v_mul_f32_e32 v14, v8, v132
	v_mov_b32_e32 v8, v9
	v_mov_b32_e32 v9, v10
	v_accvgpr_read_b32 v1, a125
	v_accvgpr_read_b32 v2, a126
	v_accvgpr_read_b32 v3, a127
	v_accvgpr_read_b32 v7, a115
	v_accvgpr_read_b32 v11, a99
	v_accvgpr_read_b32 v15, a83
	v_accvgpr_read_b32 v19, a63
	v_accvgpr_read_b32 v23, a51
	v_accvgpr_read_b32 v27, a35
	v_accvgpr_read_b32 v51, a59
	v_accvgpr_read_b32 v168, a28
	v_mul_f32_e32 v142, v47, v136
	v_pk_mul_f32 v[46:47], v[28:29], v[132:133] op_sel_hi:[1,0]
	v_pk_mul_f32 v[28:29], v[24:25], v[132:133] op_sel_hi:[1,0]
	v_pk_mul_f32 v[24:25], v[20:21], v[132:133] op_sel_hi:[1,0]
	v_pk_mul_f32 v[20:21], v[16:17], v[132:133] op_sel_hi:[1,0]
	v_pk_mul_f32 v[16:17], v[12:13], v[132:133] op_sel_hi:[1,0]
	v_pk_mul_f32 v[12:13], v[8:9], v[132:133] op_sel_hi:[1,0]
	v_mul_f32_e32 v8, v4, v132
	v_mov_b32_e32 v4, v5
	v_mov_b32_e32 v5, v6
	v_mul_f32_e32 v166, v123, v136
	v_mul_f32_e32 v122, v168, v136
	v_mul_f32_e32 v161, v171, v136
	v_mul_f32_e32 v154, v135, v136
	v_mul_f32_e32 v146, v51, v136
	v_pk_mul_f32 v[40:41], v[40:41], v[136:137] op_sel_hi:[1,0]
	v_mul_f32_e32 v36, v36, v136
	v_pk_mul_f32 v[42:43], v[42:43], v[136:137] op_sel_hi:[1,0]
	v_mul_f32_e32 v32, v32, v136
	v_pk_mul_f32 v[38:39], v[38:39], v[136:137] op_sel_hi:[1,0]
	v_mul_f32_e32 v167, v31, v132
	v_mul_f32_e32 v165, v27, v132
	v_mul_f32_e32 v159, v23, v132
	v_mul_f32_e32 v149, v19, v132
	v_mul_f32_e32 v144, v15, v132
	v_mul_f32_e32 v140, v11, v132
	v_pk_mul_f32 v[4:5], v[4:5], v[132:133] op_sel_hi:[1,0]
	v_mul_f32_e32 v137, v7, v132
	v_pk_mul_f32 v[0:1], v[0:1], v[132:133] op_sel_hi:[1,0]
	s_andn2_b64 vcc, exec, s[62:63]
	v_pk_mul_f32 v[2:3], v[2:3], v[132:133] op_sel_hi:[1,0]
	s_cbranch_vccnz .LBB0_1980
; __device__ __forceinline__ void attn_phase(const Params& p, char* smem, int coff) {
;     ...
; #pragma unroll
;         for (int nq = 0; nq < 4; ++nq) {
;           hf* dst = mix + (size_t)(s0 + q0 + wv * 64 + nq * 16 + fr) * 2048 + 1024 + h * 128 + fq * 4;
;           float ss = 0.f;
; #pragma unroll
;           for (int md = 0; md < 8; ++md) {
;             h4 o0 = *(const h4*)(dst + md * 16);
; #pragma unroll
;             for (int j = 0; j < 4; ++j) { float o = (float)o0[j] - lam * oacc[md][nq][j]; oacc[md][nq][j] = o; ss += o * o; }
;           }
	v_accvgpr_read_b32 v247, a225
	v_accvgpr_read_b32 v246, a224
	global_load_dwordx2 v[6:7], v[246:247], off offset:2272
	global_load_dwordx2 v[10:11], v[246:247], off offset:2048
	global_load_dwordx2 v[168:169], v[246:247], off offset:2080
	global_load_dwordx2 v[170:171], v[246:247], off offset:2112
	global_load_dwordx2 v[172:173], v[246:247], off offset:2144
	global_load_dwordx2 v[174:175], v[246:247], off offset:2176
	global_load_dwordx2 v[176:177], v[246:247], off offset:2208
	global_load_dwordx2 v[178:179], v[246:247], off offset:2240
	v_mov_b32_e32 v9, v224
	global_load_dwordx4 v[132:135], v[200:201], off
	v_pk_mov_b32 v[182:183], v[118:119], v[118:119] op_sel:[1,0]
	v_pk_mov_b32 v[180:181], v[88:89], v[88:89] op_sel:[1,0]
	v_mov_b32_e32 v117, v183
	v_mov_b32_e32 v87, v181
	v_mov_b32_e32 v181, v147
	v_mov_b32_e32 v183, v160
	v_pk_mov_b32 v[184:185], v[100:101], v[100:101] op_sel:[1,0]
	v_pk_mov_b32 v[186:187], v[76:77], v[76:77] op_sel:[1,0]
	v_mov_b32_e32 v109, v185
	v_mov_b32_e32 v185, v151
	v_mov_b32_e32 v85, v187
	v_mov_b32_e32 v187, v145
	v_pk_mov_b32 v[188:189], v[68:69], v[68:69] op_sel:[1,0]
	v_pk_mov_b32 v[190:191], v[60:61], v[60:61] op_sel:[1,0]
	v_mov_b32_e32 v71, v189
	v_mov_b32_e32 v189, v141
	v_mov_b32_e32 v63, v191
	v_mov_b32_e32 v191, v138
	v_pk_mov_b32 v[194:195], v[52:53], v[52:53] op_sel:[1,0]
	v_pk_mov_b32 v[242:243], v[102:103], v[102:103] op_sel:[1,0]
	v_mov_b32_e32 v55, v195
	v_mov_b32_e32 v195, v152
	v_mov_b32_e32 v83, v243
	v_mov_b32_e32 v243, v153
	v_lshlrev_b32_e32 v9, 2, v9
	v_bitop3_b32 v9, v9, s3, v226 bitop3:0x6c
	v_accvgpr_read_b32 v249, a227
	v_accvgpr_read_b32 v248, a226
	s_waitcnt vmcnt(8)
	v_cvt_f32_f16_sdwa v205, v7 dst_sel:DWORD dst_unused:UNUSED_PAD src0_sel:WORD_1
	s_waitcnt vmcnt(7)
	v_cvt_f32_f16_sdwa v211, v10 dst_sel:DWORD dst_unused:UNUSED_PAD src0_sel:WORD_1
	v_cvt_f32_f16_e32 v210, v10
	v_cvt_f32_f16_e32 v204, v7
	v_cvt_f32_f16_sdwa v213, v11 dst_sel:DWORD dst_unused:UNUSED_PAD src0_sel:WORD_1
	v_cvt_f32_f16_e32 v212, v11
	s_waitcnt vmcnt(6)
	v_cvt_f32_f16_sdwa v215, v168 dst_sel:DWORD dst_unused:UNUSED_PAD src0_sel:WORD_1
	v_cvt_f32_f16_e32 v214, v168
	v_cvt_f32_f16_sdwa v217, v169 dst_sel:DWORD dst_unused:UNUSED_PAD src0_sel:WORD_1
	v_cvt_f32_f16_e32 v216, v169
	s_waitcnt vmcnt(5)
	v_cvt_f32_f16_sdwa v169, v170 dst_sel:DWORD dst_unused:UNUSED_PAD src0_sel:WORD_1
	v_cvt_f32_f16_e32 v168, v170
	v_cvt_f32_f16_sdwa v219, v171 dst_sel:DWORD dst_unused:UNUSED_PAD src0_sel:WORD_1
	v_cvt_f32_f16_e32 v218, v171
	s_waitcnt vmcnt(4)
	v_cvt_f32_f16_sdwa v171, v172 dst_sel:DWORD dst_unused:UNUSED_PAD src0_sel:WORD_1
	v_cvt_f32_f16_e32 v170, v172
	v_cvt_f32_f16_sdwa v221, v173 dst_sel:DWORD dst_unused:UNUSED_PAD src0_sel:WORD_1
	v_cvt_f32_f16_e32 v220, v173
	s_waitcnt vmcnt(3)
	v_cvt_f32_f16_sdwa v173, v174 dst_sel:DWORD dst_unused:UNUSED_PAD src0_sel:WORD_1
	v_cvt_f32_f16_e32 v172, v174
	v_cvt_f32_f16_sdwa v229, v175 dst_sel:DWORD dst_unused:UNUSED_PAD src0_sel:WORD_1
	v_cvt_f32_f16_e32 v228, v175
	s_waitcnt vmcnt(2)
	v_cvt_f32_f16_sdwa v175, v176 dst_sel:DWORD dst_unused:UNUSED_PAD src0_sel:WORD_1
	v_cvt_f32_f16_e32 v174, v176
	v_cvt_f32_f16_sdwa v231, v177 dst_sel:DWORD dst_unused:UNUSED_PAD src0_sel:WORD_1
	v_cvt_f32_f16_e32 v230, v177
	v_pk_fma_f32 v[176:177], v[192:193], v[116:117], v[210:211] neg_lo:[1,0,0] neg_hi:[1,0,0]
	v_pk_fma_f32 v[10:11], v[192:193], v[180:181], v[204:205] neg_lo:[1,0,0] neg_hi:[1,0,0]
	v_pk_fma_f32 v[180:181], v[192:193], v[182:183], v[212:213] neg_lo:[1,0,0] neg_hi:[1,0,0]
	v_pk_mul_f32 v[210:211], v[176:177], v[176:177]
	v_pk_mul_f32 v[212:213], v[180:181], v[180:181]
	v_add_f32_e32 v15, v210, v211
	v_pk_fma_f32 v[182:183], v[192:193], v[108:109], v[214:215] neg_lo:[1,0,0] neg_hi:[1,0,0]
	v_add_f32_e32 v15, v212, v15
	v_pk_mul_f32 v[214:215], v[182:183], v[182:183]
	v_add_f32_e32 v15, v213, v15
	v_pk_fma_f32 v[184:185], v[192:193], v[184:185], v[216:217] neg_lo:[1,0,0] neg_hi:[1,0,0]
	v_add_f32_e32 v15, v214, v15
	v_pk_mul_f32 v[216:217], v[184:185], v[184:185]
	v_add_f32_e32 v15, v215, v15
	v_pk_fma_f32 v[168:169], v[192:193], v[84:85], v[168:169] neg_lo:[1,0,0] neg_hi:[1,0,0]
	v_add_f32_e32 v15, v216, v15
	v_pk_fma_f32 v[186:187], v[192:193], v[186:187], v[218:219] neg_lo:[1,0,0] neg_hi:[1,0,0]
	v_pk_mul_f32 v[218:219], v[168:169], v[168:169]
	v_add_f32_e32 v15, v217, v15
	v_add_f32_e32 v15, v218, v15
	v_pk_fma_f32 v[188:189], v[192:193], v[188:189], v[220:221] neg_lo:[1,0,0] neg_hi:[1,0,0]
	v_pk_mul_f32 v[220:221], v[186:187], v[186:187]
	v_add_f32_e32 v15, v219, v15
	v_pk_fma_f32 v[170:171], v[192:193], v[70:71], v[170:171] neg_lo:[1,0,0] neg_hi:[1,0,0]
	v_add_f32_e32 v15, v220, v15
	v_pk_fma_f32 v[190:191], v[192:193], v[190:191], v[228:229] neg_lo:[1,0,0] neg_hi:[1,0,0]
	v_pk_mul_f32 v[228:229], v[170:171], v[170:171]
	v_add_f32_e32 v15, v221, v15
	v_add_f32_e32 v15, v228, v15
	v_pk_mul_f32 v[232:233], v[188:189], v[188:189]
	v_add_f32_e32 v15, v229, v15
	v_pk_fma_f32 v[172:173], v[192:193], v[62:63], v[172:173] neg_lo:[1,0,0] neg_hi:[1,0,0]
	v_add_f32_e32 v15, v232, v15
	v_pk_mul_f32 v[234:235], v[172:173], v[172:173]
	v_add_f32_e32 v15, v233, v15
	v_add_f32_e32 v15, v234, v15
	v_pk_mul_f32 v[236:237], v[190:191], v[190:191]
	v_add_f32_e32 v15, v235, v15
	v_pk_fma_f32 v[174:175], v[192:193], v[54:55], v[174:175] neg_lo:[1,0,0] neg_hi:[1,0,0]
	s_waitcnt vmcnt(1)
; __device__ __forceinline__ void attn_phase(const Params& p, char* smem, int coff) {
;     ...
;           }
;           ss += shx(ss, 16); ss += shx(ss, 32);
;           const float r = rsqrtf(ss * (1.f / 128.f) + 1e-5f) * (1.f - 0.35550906759f);
; #pragma unroll
;           for (int md = 0; md < 8; ++md) {
;             f4 gg = *(const f4*)(p.in[41] + md * 16 + fq * 4); h4 o;
; #pragma unroll
;             for (int j = 0; j < 4; ++j) o[j] = (hf)(oacc[md][nq][j] * r * gg[j]);
;             *(h4*)(dst + md * 16) = o;
;           }
;         }
	v_cvt_f32_f16_sdwa v241, v178 dst_sel:DWORD dst_unused:UNUSED_PAD src0_sel:WORD_1
	v_cvt_f32_f16_e32 v240, v178
	v_add_f32_e32 v15, v236, v15
	v_pk_mul_f32 v[238:239], v[174:175], v[174:175]
	v_add_f32_e32 v15, v237, v15
	v_pk_fma_f32 v[194:195], v[192:193], v[194:195], v[230:231] neg_lo:[1,0,0] neg_hi:[1,0,0]
	v_cvt_f32_f16_sdwa v245, v179 dst_sel:DWORD dst_unused:UNUSED_PAD src0_sel:WORD_1
	v_cvt_f32_f16_e32 v244, v179
	v_add_f32_e32 v15, v238, v15
	v_pk_mul_f32 v[230:231], v[194:195], v[194:195]
	v_add_f32_e32 v15, v239, v15
	v_cvt_f32_f16_sdwa v203, v6 dst_sel:DWORD dst_unused:UNUSED_PAD src0_sel:WORD_1
	v_cvt_f32_f16_e32 v202, v6
	v_pk_fma_f32 v[178:179], v[192:193], v[82:83], v[240:241] neg_lo:[1,0,0] neg_hi:[1,0,0]
	v_add_f32_e32 v15, v230, v15
	v_pk_mul_f32 v[240:241], v[178:179], v[178:179]
	v_add_f32_e32 v15, v231, v15
	v_pk_fma_f32 v[242:243], v[192:193], v[242:243], v[244:245] neg_lo:[1,0,0] neg_hi:[1,0,0]
	v_add_f32_e32 v15, v240, v15
	v_pk_mul_f32 v[244:245], v[242:243], v[242:243]
	v_add_f32_e32 v15, v241, v15
	v_pk_fma_f32 v[6:7], v[192:193], v[86:87], v[202:203] neg_lo:[1,0,0] neg_hi:[1,0,0]
	v_add_f32_e32 v15, v244, v15
	v_pk_mul_f32 v[202:203], v[6:7], v[6:7]
	v_add_f32_e32 v15, v245, v15
	v_add_f32_e32 v15, v202, v15
	v_pk_mul_f32 v[204:205], v[10:11], v[10:11]
	v_add_f32_e32 v15, v203, v15
	v_add_f32_e32 v15, v204, v15
	v_add_f32_e32 v15, v205, v15
	ds_swizzle_b32 v19, v15 offset:swizzle(SWAP,16)
	v_mov_b32_e32 v55, 0x3727c5ac
	v_pk_mov_b32 v[204:205], v[64:65], v[64:65] op_sel:[1,0]
	v_pk_mov_b32 v[212:213], v[112:113], v[112:113] op_sel:[1,0]
	v_mov_b32_e32 v67, v205
	s_waitcnt lgkmcnt(0)
	v_add_f32_e32 v15, v15, v19
	ds_bpermute_b32 v9, v9, v15
	v_mov_b32_e32 v205, v139
	v_mov_b32_e32 v93, v213
	v_mov_b32_e32 v213, v158
	v_pk_mov_b32 v[202:203], v[72:73], v[72:73] op_sel:[1,0]
	s_waitcnt lgkmcnt(0)
	v_add_f32_e32 v9, v15, v9
	v_fmamk_f32 v9, v9, 0x3c000000, v55
	v_mul_f32_e32 v15, 0x4b800000, v9
	v_cmp_gt_f32_e32 vcc, s83, v9
	v_mov_b32_e32 v75, v203
	v_mov_b32_e32 v203, v143
	v_cndmask_b32_e32 v9, v9, v15, vcc
	v_rsq_f32_e32 v9, v9
	v_pk_mov_b32 v[210:211], v[56:57], v[56:57] op_sel:[1,0]
	v_mul_f32_e32 v15, 0x45800000, v9
	v_cndmask_b32_e32 v9, v9, v15, vcc
	v_mul_f32_e32 v136, 0x3f24fd5c, v9
	v_pk_mul_f32 v[176:177], v[176:177], v[136:137] op_sel_hi:[1,0]
	v_pk_mul_f32 v[168:169], v[168:169], v[136:137] op_sel_hi:[1,0]
	s_waitcnt vmcnt(0)
	v_pk_mul_f32 v[132:133], v[132:133], v[176:177]
	v_pk_mul_f32 v[176:177], v[180:181], v[136:137] op_sel_hi:[1,0]
	v_cvt_pk_f16_f32 v132, v132, v133
	v_pk_mul_f32 v[134:135], v[134:135], v[176:177]
	v_pk_mul_f32 v[176:177], v[182:183], v[136:137] op_sel_hi:[1,0]
	v_cvt_pk_f16_f32 v133, v134, v135
	global_store_dwordx2 v[246:247], v[132:133], off offset:2048
	global_load_dwordx4 v[132:135], v[200:201], off offset:64
	v_pk_mul_f32 v[180:181], v[184:185], v[136:137] op_sel_hi:[1,0]
	v_pk_mul_f32 v[6:7], v[6:7], v[136:137] op_sel_hi:[1,0]
	v_pk_mul_f32 v[10:11], v[10:11], v[136:137] op_sel_hi:[1,0]
	v_mov_b32_e32 v9, v224
	v_mov_b32_e32 v59, v211
	v_mov_b32_e32 v211, v157
	s_waitcnt vmcnt(0)
	v_pk_mul_f32 v[132:133], v[132:133], v[176:177]
	v_pk_mul_f32 v[134:135], v[134:135], v[180:181]
	v_cvt_pk_f16_f32 v132, v132, v133
	v_cvt_pk_f16_f32 v133, v134, v135
	global_store_dwordx2 v[246:247], v[132:133], off offset:2080
	global_load_dwordx4 v[132:135], v[200:201], off offset:128
	v_pk_mul_f32 v[176:177], v[186:187], v[136:137] op_sel_hi:[1,0]
	s_waitcnt vmcnt(0)
	v_pk_mul_f32 v[132:133], v[132:133], v[168:169]
	v_pk_mul_f32 v[134:135], v[134:135], v[176:177]
	v_cvt_pk_f16_f32 v132, v132, v133
	v_cvt_pk_f16_f32 v133, v134, v135
	global_store_dwordx2 v[246:247], v[132:133], off offset:2112
	global_load_dwordx4 v[132:135], v[200:201], off offset:192
	v_pk_mul_f32 v[168:169], v[170:171], v[136:137] op_sel_hi:[1,0]
	v_pk_mul_f32 v[170:171], v[188:189], v[136:137] op_sel_hi:[1,0]
	s_waitcnt vmcnt(0)
	v_pk_mul_f32 v[132:133], v[132:133], v[168:169]
	v_pk_mul_f32 v[134:135], v[134:135], v[170:171]
	v_cvt_pk_f16_f32 v132, v132, v133
	v_cvt_pk_f16_f32 v133, v134, v135
	global_store_dwordx2 v[246:247], v[132:133], off offset:2144
	global_load_dwordx4 v[132:135], v[200:201], off offset:256
	v_pk_mul_f32 v[168:169], v[172:173], v[136:137] op_sel_hi:[1,0]
	v_pk_mul_f32 v[170:171], v[190:191], v[136:137] op_sel_hi:[1,0]
	v_pk_mov_b32 v[190:191], v[110:111], v[110:111] op_sel:[1,0]
	s_waitcnt vmcnt(0)
	v_pk_mul_f32 v[132:133], v[132:133], v[168:169]
	v_pk_mul_f32 v[134:135], v[134:135], v[170:171]
	v_cvt_pk_f16_f32 v132, v132, v133
	v_cvt_pk_f16_f32 v133, v134, v135
	global_store_dwordx2 v[246:247], v[132:133], off offset:2176
	global_load_dwordx4 v[132:135], v[200:201], off offset:320
	v_pk_mul_f32 v[168:169], v[174:175], v[136:137] op_sel_hi:[1,0]
	v_pk_mul_f32 v[170:171], v[194:195], v[136:137] op_sel_hi:[1,0]
	v_mov_b32_e32 v115, v191
	v_mov_b32_e32 v191, v156
	v_pk_mov_b32 v[194:195], v[90:91], v[90:91] op_sel:[1,0]
	s_waitcnt vmcnt(0)
	v_pk_mul_f32 v[132:133], v[132:133], v[168:169]
	v_pk_mul_f32 v[134:135], v[134:135], v[170:171]
	v_cvt_pk_f16_f32 v132, v132, v133
	v_cvt_pk_f16_f32 v133, v134, v135
	global_store_dwordx2 v[246:247], v[132:133], off offset:2208
	global_load_dwordx4 v[132:135], v[200:201], off offset:384
	v_pk_mul_f32 v[168:169], v[178:179], v[136:137] op_sel_hi:[1,0]
	v_pk_mul_f32 v[170:171], v[242:243], v[136:137] op_sel_hi:[1,0]
	global_load_dwordx2 v[172:173], v[248:249], off offset:2272
	global_load_dwordx2 v[174:175], v[248:249], off offset:2048
	global_load_dwordx2 v[176:177], v[248:249], off offset:2080
	global_load_dwordx2 v[180:181], v[248:249], off offset:2112
	global_load_dwordx2 v[182:183], v[248:249], off offset:2144
	global_load_dwordx2 v[184:185], v[248:249], off offset:2176
	global_load_dwordx2 v[186:187], v[248:249], off offset:2208
	global_load_dwordx2 v[188:189], v[248:249], off offset:2240
	v_pk_mov_b32 v[178:179], v[126:127], v[126:127] op_sel:[1,0]
	v_mov_b32_e32 v95, v195
	v_mov_b32_e32 v125, v179
	v_mov_b32_e32 v179, v164
	v_mov_b32_e32 v195, v148
	s_waitcnt vmcnt(7)
; __device__ __forceinline__ void attn_phase(const Params& p, char* smem, int coff) {
;     ...
; #pragma unroll
;         for (int nq = 0; nq < 4; ++nq) {
;           hf* dst = mix + (size_t)(s0 + q0 + wv * 64 + nq * 16 + fr) * 2048 + 1024 + h * 128 + fq * 4;
;           float ss = 0.f;
; #pragma unroll
;           for (int md = 0; md < 8; ++md) {
;             h4 o0 = *(const h4*)(dst + md * 16);
; #pragma unroll
;             for (int j = 0; j < 4; ++j) { float o = (float)o0[j] - lam * oacc[md][nq][j]; oacc[md][nq][j] = o; ss += o * o; }
;           }
;           ss += shx(ss, 16); ss += shx(ss, 32);
;           const float r = rsqrtf(ss * (1.f / 128.f) + 1e-5f) * (1.f - 0.35550906759f);
; #pragma unroll
;           for (int md = 0; md < 8; ++md) {
;             f4 gg = *(const f4*)(p.in[41] + md * 16 + fq * 4); h4 o;
; #pragma unroll
;             for (int j = 0; j < 4; ++j) o[j] = (hf)(oacc[md][nq][j] * r * gg[j]);
;             *(h4*)(dst + md * 16) = o;
;           }
;         }
	v_cvt_f32_f16_sdwa v215, v173 dst_sel:DWORD dst_unused:UNUSED_PAD src0_sel:WORD_1
	v_cvt_f32_f16_e32 v214, v173
	s_waitcnt vmcnt(6)
	v_cvt_f32_f16_sdwa v173, v174 dst_sel:DWORD dst_unused:UNUSED_PAD src0_sel:WORD_1
	v_cvt_f32_f16_sdwa v217, v175 dst_sel:DWORD dst_unused:UNUSED_PAD src0_sel:WORD_1
	v_pk_mul_f32 v[132:133], v[132:133], v[168:169]
	v_pk_mul_f32 v[134:135], v[134:135], v[170:171]
	v_cvt_pk_f16_f32 v132, v132, v133
	v_cvt_pk_f16_f32 v133, v134, v135
	global_store_dwordx2 v[246:247], v[132:133], off offset:2240
	global_load_dwordx4 v[168:171], v[200:201], off offset:448
	v_cvt_f32_f16_sdwa v133, v172 dst_sel:DWORD dst_unused:UNUSED_PAD src0_sel:WORD_1
	v_cvt_f32_f16_e32 v132, v172
	v_cvt_f32_f16_e32 v172, v174
	v_cvt_f32_f16_e32 v216, v175
	s_waitcnt vmcnt(4)
	v_cvt_f32_f16_sdwa v231, v185 dst_sel:DWORD dst_unused:UNUSED_PAD src0_sel:WORD_1
	v_cvt_f32_f16_e32 v230, v185
	s_waitcnt vmcnt(2)
	v_cvt_f32_f16_sdwa v235, v189 dst_sel:DWORD dst_unused:UNUSED_PAD src0_sel:WORD_1
	v_cvt_f32_f16_e32 v234, v189
	v_cvt_f32_f16_sdwa v175, v176 dst_sel:DWORD dst_unused:UNUSED_PAD src0_sel:WORD_1
	v_cvt_f32_f16_e32 v174, v176
	v_pk_mov_b32 v[134:135], v[98:99], v[98:99] op_sel:[1,0]
	v_pk_fma_f32 v[172:173], v[192:193], v[124:125], v[172:173] neg_lo:[1,0,0] neg_hi:[1,0,0]
	v_mov_b32_e32 v97, v135
	v_mov_b32_e32 v135, v150
	v_cvt_f32_f16_sdwa v219, v177 dst_sel:DWORD dst_unused:UNUSED_PAD src0_sel:WORD_1
	v_cvt_f32_f16_e32 v218, v177
	v_pk_fma_f32 v[178:179], v[192:193], v[178:179], v[216:217] neg_lo:[1,0,0] neg_hi:[1,0,0]
	v_pk_fma_f32 v[134:135], v[192:193], v[134:135], v[214:215] neg_lo:[1,0,0] neg_hi:[1,0,0]
	v_pk_mul_f32 v[214:215], v[178:179], v[178:179]
	v_cvt_f32_f16_sdwa v177, v180 dst_sel:DWORD dst_unused:UNUSED_PAD src0_sel:WORD_1
	v_cvt_f32_f16_e32 v176, v180
	v_pk_fma_f32 v[174:175], v[192:193], v[114:115], v[174:175] neg_lo:[1,0,0] neg_hi:[1,0,0]
	v_cvt_f32_f16_sdwa v221, v181 dst_sel:DWORD dst_unused:UNUSED_PAD src0_sel:WORD_1
	v_cvt_f32_f16_e32 v220, v181
	v_pk_mul_f32 v[216:217], v[174:175], v[174:175]
	v_cvt_f32_f16_sdwa v181, v182 dst_sel:DWORD dst_unused:UNUSED_PAD src0_sel:WORD_1
	v_cvt_f32_f16_e32 v180, v182
	v_cvt_f32_f16_sdwa v229, v183 dst_sel:DWORD dst_unused:UNUSED_PAD src0_sel:WORD_1
	v_cvt_f32_f16_e32 v228, v183
	v_cvt_f32_f16_sdwa v183, v184 dst_sel:DWORD dst_unused:UNUSED_PAD src0_sel:WORD_1
	v_cvt_f32_f16_e32 v182, v184
	v_cvt_f32_f16_sdwa v185, v186 dst_sel:DWORD dst_unused:UNUSED_PAD src0_sel:WORD_1
	v_cvt_f32_f16_e32 v184, v186
	v_cvt_f32_f16_sdwa v233, v187 dst_sel:DWORD dst_unused:UNUSED_PAD src0_sel:WORD_1
	v_cvt_f32_f16_e32 v232, v187
	v_cvt_f32_f16_sdwa v187, v188 dst_sel:DWORD dst_unused:UNUSED_PAD src0_sel:WORD_1
	v_cvt_f32_f16_e32 v186, v188
	v_pk_fma_f32 v[188:189], v[192:193], v[190:191], v[218:219] neg_lo:[1,0,0] neg_hi:[1,0,0]
	v_pk_fma_f32 v[176:177], v[192:193], v[94:95], v[176:177] neg_lo:[1,0,0] neg_hi:[1,0,0]
	v_pk_mul_f32 v[218:219], v[188:189], v[188:189]
	v_pk_fma_f32 v[190:191], v[192:193], v[194:195], v[220:221] neg_lo:[1,0,0] neg_hi:[1,0,0]
	v_pk_mul_f32 v[220:221], v[176:177], v[176:177]
	v_pk_fma_f32 v[194:195], v[192:193], v[202:203], v[228:229] neg_lo:[1,0,0] neg_hi:[1,0,0]
	v_pk_mul_f32 v[228:229], v[190:191], v[190:191]
	v_pk_fma_f32 v[180:181], v[192:193], v[74:75], v[180:181] neg_lo:[1,0,0] neg_hi:[1,0,0]
	v_pk_fma_f32 v[202:203], v[192:193], v[210:211], v[232:233] neg_lo:[1,0,0] neg_hi:[1,0,0]
	v_pk_mul_f32 v[232:233], v[194:195], v[194:195]
	v_pk_fma_f32 v[182:183], v[192:193], v[66:67], v[182:183] neg_lo:[1,0,0] neg_hi:[1,0,0]
	v_pk_fma_f32 v[184:185], v[192:193], v[58:59], v[184:185] neg_lo:[1,0,0] neg_hi:[1,0,0]
	v_pk_mul_f32 v[240:241], v[202:203], v[202:203]
	v_pk_mul_f32 v[238:239], v[184:185], v[184:185]
	v_pk_fma_f32 v[186:187], v[192:193], v[92:93], v[186:187] neg_lo:[1,0,0] neg_hi:[1,0,0]
	v_pk_fma_f32 v[132:133], v[192:193], v[96:97], v[132:133] neg_lo:[1,0,0] neg_hi:[1,0,0]
	v_pk_mul_f32 v[242:243], v[186:187], v[186:187]
	v_pk_mul_f32 v[210:211], v[134:135], v[134:135]
	s_waitcnt vmcnt(0)
	v_pk_mul_f32 v[6:7], v[168:169], v[6:7]
	v_pk_mul_f32 v[10:11], v[170:171], v[10:11]
	v_cvt_pk_f16_f32 v6, v6, v7
	v_cvt_pk_f16_f32 v7, v10, v11
	global_store_dwordx2 v[246:247], v[6:7], off offset:2272
	global_load_dwordx4 v[168:171], v[200:201], off
	v_pk_fma_f32 v[10:11], v[192:193], v[204:205], v[230:231] neg_lo:[1,0,0] neg_hi:[1,0,0]
	v_pk_fma_f32 v[204:205], v[192:193], v[212:213], v[234:235] neg_lo:[1,0,0] neg_hi:[1,0,0]
	v_pk_mul_f32 v[212:213], v[172:173], v[172:173]
	v_pk_mul_f32 v[230:231], v[180:181], v[180:181]
	v_add_f32_e32 v15, v212, v213
	v_add_f32_e32 v15, v214, v15
	v_add_f32_e32 v15, v215, v15
	v_add_f32_e32 v15, v216, v15
	v_add_f32_e32 v15, v217, v15
	v_add_f32_e32 v15, v218, v15
	v_add_f32_e32 v15, v219, v15
	v_add_f32_e32 v15, v220, v15
	v_add_f32_e32 v15, v221, v15
	v_add_f32_e32 v15, v228, v15
	v_add_f32_e32 v15, v229, v15
	v_add_f32_e32 v15, v230, v15
	v_add_f32_e32 v15, v231, v15
	v_add_f32_e32 v15, v232, v15
	v_pk_mul_f32 v[234:235], v[182:183], v[182:183]
	v_add_f32_e32 v15, v233, v15
	v_add_f32_e32 v15, v234, v15
	v_pk_mul_f32 v[236:237], v[10:11], v[10:11]
	v_add_f32_e32 v15, v235, v15
	v_add_f32_e32 v15, v236, v15
	v_add_f32_e32 v15, v237, v15
	v_add_f32_e32 v15, v238, v15
	v_add_f32_e32 v15, v239, v15
	v_add_f32_e32 v15, v240, v15
	v_add_f32_e32 v15, v241, v15
	v_add_f32_e32 v15, v242, v15
	v_pk_mul_f32 v[244:245], v[204:205], v[204:205]
	v_add_f32_e32 v15, v243, v15
	v_add_f32_e32 v15, v244, v15
	v_pk_mul_f32 v[6:7], v[132:133], v[132:133]
	v_add_f32_e32 v15, v245, v15
	v_add_f32_e32 v6, v6, v15
	v_add_f32_e32 v6, v7, v6
	v_add_f32_e32 v6, v210, v6
	v_add_f32_e32 v6, v211, v6
	ds_swizzle_b32 v7, v6 offset:swizzle(SWAP,16)
	v_pk_mov_b32 v[212:213], v[42:43], v[42:43] op_sel:[1,0]
	v_pk_mov_b32 v[210:211], v[40:41], v[40:41] op_sel:[1,0]
	v_mov_b32_e32 v37, v213
	v_mov_b32_e32 v213, v163
	s_waitcnt lgkmcnt(0)
; __device__ __forceinline__ void attn_phase(const Params& p, char* smem, int coff) {
;     ...
;           }
;           ss += shx(ss, 16); ss += shx(ss, 32);
;           const float r = rsqrtf(ss * (1.f / 128.f) + 1e-5f) * (1.f - 0.35550906759f);
; #pragma unroll
;           for (int md = 0; md < 8; ++md) {
;             f4 gg = *(const f4*)(p.in[41] + md * 16 + fq * 4); h4 o;
; #pragma unroll
;             for (int j = 0; j < 4; ++j) o[j] = (hf)(oacc[md][nq][j] * r * gg[j]);
;             *(h4*)(dst + md * 16) = o;
;           }
;         }
	v_add_f32_e32 v6, v6, v7
	v_lshlrev_b32_e32 v7, 2, v9
	v_bitop3_b32 v7, v7, s3, v226 bitop3:0x6c
	ds_bpermute_b32 v7, v7, v6
	v_mov_b32_e32 v9, v224
	v_mov_b32_e32 v45, v211
	v_mov_b32_e32 v211, v162
	s_waitcnt lgkmcnt(0)
	v_add_f32_e32 v6, v6, v7
	v_fmamk_f32 v6, v6, 0x3c000000, v55
	v_mul_f32_e32 v7, 0x4b800000, v6
	v_cmp_gt_f32_e32 vcc, s83, v6
	s_nop 1
	v_cndmask_b32_e32 v6, v6, v7, vcc
	v_rsq_f32_e32 v6, v6
	s_nop 0
	v_mul_f32_e32 v7, 0x45800000, v6
	v_cndmask_b32_e32 v6, v6, v7, vcc
	v_mul_f32_e32 v6, 0x3f24fd5c, v6
	v_pk_mul_f32 v[172:173], v[172:173], v[6:7] op_sel_hi:[1,0]
	v_pk_mul_f32 v[178:179], v[178:179], v[6:7] op_sel_hi:[1,0]
	v_pk_mul_f32 v[10:11], v[10:11], v[6:7] op_sel_hi:[1,0]
	v_pk_mul_f32 v[186:187], v[186:187], v[6:7] op_sel_hi:[1,0]
	v_pk_mul_f32 v[132:133], v[132:133], v[6:7] op_sel_hi:[1,0]
	v_pk_mul_f32 v[134:135], v[134:135], v[6:7] op_sel_hi:[1,0]
	s_waitcnt vmcnt(0)
	v_pk_mul_f32 v[168:169], v[168:169], v[172:173]
	v_pk_mul_f32 v[170:171], v[170:171], v[178:179]
	v_cvt_pk_f16_f32 v168, v168, v169
	v_cvt_pk_f16_f32 v169, v170, v171
	global_store_dwordx2 v[248:249], v[168:169], off offset:2048
	global_load_dwordx4 v[168:171], v[200:201], off offset:64
	v_pk_mul_f32 v[172:173], v[174:175], v[6:7] op_sel_hi:[1,0]
	v_pk_mul_f32 v[174:175], v[188:189], v[6:7] op_sel_hi:[1,0]
	v_pk_mul_f32 v[188:189], v[204:205], v[6:7] op_sel_hi:[1,0]
	v_pk_mov_b32 v[204:205], v[48:49], v[48:49] op_sel:[1,0]
	s_waitcnt vmcnt(0)
	v_pk_mul_f32 v[168:169], v[168:169], v[172:173]
	v_pk_mul_f32 v[170:171], v[170:171], v[174:175]
	v_cvt_pk_f16_f32 v168, v168, v169
	v_cvt_pk_f16_f32 v169, v170, v171
	global_store_dwordx2 v[248:249], v[168:169], off offset:2080
	global_load_dwordx4 v[168:171], v[200:201], off offset:128
	v_pk_mul_f32 v[172:173], v[176:177], v[6:7] op_sel_hi:[1,0]
	v_pk_mul_f32 v[174:175], v[190:191], v[6:7] op_sel_hi:[1,0]
	v_mov_b32_e32 v51, v205
	v_mov_b32_e32 v205, v142
	v_pk_mov_b32 v[190:191], v[120:121], v[120:121] op_sel:[1,0]
	s_waitcnt vmcnt(0)
	v_pk_mul_f32 v[168:169], v[168:169], v[172:173]
	v_pk_mul_f32 v[170:171], v[170:171], v[174:175]
	v_cvt_pk_f16_f32 v168, v168, v169
	v_cvt_pk_f16_f32 v169, v170, v171
	global_store_dwordx2 v[248:249], v[168:169], off offset:2112
	global_load_dwordx4 v[168:171], v[200:201], off offset:192
	v_pk_mul_f32 v[172:173], v[180:181], v[6:7] op_sel_hi:[1,0]
	v_pk_mul_f32 v[174:175], v[194:195], v[6:7] op_sel_hi:[1,0]
	v_mov_b32_e32 v123, v191
	v_mov_b32_e32 v191, v161
	v_pk_mov_b32 v[194:195], v[104:105], v[104:105] op_sel:[1,0]
	s_waitcnt vmcnt(0)
	v_pk_mul_f32 v[168:169], v[168:169], v[172:173]
	v_pk_mul_f32 v[170:171], v[170:171], v[174:175]
	v_cvt_pk_f16_f32 v168, v168, v169
	v_cvt_pk_f16_f32 v169, v170, v171
	global_store_dwordx2 v[248:249], v[168:169], off offset:2144
	global_load_dwordx4 v[168:171], v[200:201], off offset:256
	v_pk_mul_f32 v[172:173], v[182:183], v[6:7] op_sel_hi:[1,0]
	v_mov_b32_e32 v107, v195
	v_mov_b32_e32 v195, v154
	s_waitcnt vmcnt(0)
	v_pk_mul_f32 v[168:169], v[168:169], v[172:173]
	v_pk_mul_f32 v[10:11], v[170:171], v[10:11]
	v_cvt_pk_f16_f32 v168, v168, v169
	v_cvt_pk_f16_f32 v169, v10, v11
	global_store_dwordx2 v[248:249], v[168:169], off offset:2176
	global_load_dwordx4 v[168:171], v[200:201], off offset:320
	v_pk_mul_f32 v[10:11], v[184:185], v[6:7] op_sel_hi:[1,0]
	v_pk_mul_f32 v[172:173], v[202:203], v[6:7] op_sel_hi:[1,0]
	v_pk_mov_b32 v[202:203], v[78:79], v[78:79] op_sel:[1,0]
	s_waitcnt vmcnt(0)
	v_pk_mul_f32 v[10:11], v[168:169], v[10:11]
	v_pk_mul_f32 v[168:169], v[170:171], v[172:173]
	v_cvt_pk_f16_f32 v10, v10, v11
	v_cvt_pk_f16_f32 v11, v168, v169
	global_store_dwordx2 v[248:249], v[10:11], off offset:2208
	global_load_dwordx4 v[168:171], v[200:201], off offset:384
	s_nop 0
	global_load_dwordx2 v[10:11], v[206:207], off offset:2272
	global_load_dwordx2 v[172:173], v[206:207], off offset:2048
	global_load_dwordx2 v[174:175], v[206:207], off offset:2080
	global_load_dwordx2 v[176:177], v[206:207], off offset:2112
	global_load_dwordx2 v[178:179], v[206:207], off offset:2144
	global_load_dwordx2 v[180:181], v[206:207], off offset:2176
	global_load_dwordx2 v[182:183], v[206:207], off offset:2208
	global_load_dwordx2 v[184:185], v[206:207], off offset:2240
	v_mov_b32_e32 v81, v203
	v_mov_b32_e32 v203, v146
	s_waitcnt vmcnt(8)
	v_pk_mul_f32 v[168:169], v[168:169], v[186:187]
	v_pk_mul_f32 v[170:171], v[170:171], v[188:189]
	v_cvt_pk_f16_f32 v168, v168, v169
	v_cvt_pk_f16_f32 v169, v170, v171
	global_store_dwordx2 v[248:249], v[168:169], off offset:2240
	global_load_dwordx4 v[168:171], v[200:201], off offset:448
	s_waitcnt vmcnt(8)
	v_cvt_f32_f16_sdwa v217, v172 dst_sel:DWORD dst_unused:UNUSED_PAD src0_sel:WORD_1
	v_cvt_f32_f16_e32 v216, v172
	v_cvt_f32_f16_sdwa v215, v11 dst_sel:DWORD dst_unused:UNUSED_PAD src0_sel:WORD_1
	v_cvt_f32_f16_e32 v214, v11
	v_cvt_f32_f16_sdwa v219, v173 dst_sel:DWORD dst_unused:UNUSED_PAD src0_sel:WORD_1
	v_cvt_f32_f16_e32 v218, v173
	s_waitcnt vmcnt(4)
	v_cvt_f32_f16_sdwa v233, v181 dst_sel:DWORD dst_unused:UNUSED_PAD src0_sel:WORD_1
	v_cvt_f32_f16_e32 v232, v181
	s_waitcnt vmcnt(2)
; __device__ __forceinline__ void attn_phase(const Params& p, char* smem, int coff) {
;     ...
; #pragma unroll
;         for (int nq = 0; nq < 4; ++nq) {
;           hf* dst = mix + (size_t)(s0 + q0 + wv * 64 + nq * 16 + fr) * 2048 + 1024 + h * 128 + fq * 4;
;           float ss = 0.f;
; #pragma unroll
;           for (int md = 0; md < 8; ++md) {
;             h4 o0 = *(const h4*)(dst + md * 16);
; #pragma unroll
;             for (int j = 0; j < 4; ++j) { float o = (float)o0[j] - lam * oacc[md][nq][j]; oacc[md][nq][j] = o; ss += o * o; }
;           }
;           ss += shx(ss, 16); ss += shx(ss, 32);
;           const float r = rsqrtf(ss * (1.f / 128.f) + 1e-5f) * (1.f - 0.35550906759f);
; #pragma unroll
;           for (int md = 0; md < 8; ++md) {
;             f4 gg = *(const f4*)(p.in[41] + md * 16 + fq * 4); h4 o;
; #pragma unroll
;             for (int j = 0; j < 4; ++j) o[j] = (hf)(oacc[md][nq][j] * r * gg[j]);
;             *(h4*)(dst + md * 16) = o;
	v_cvt_f32_f16_sdwa v237, v185 dst_sel:DWORD dst_unused:UNUSED_PAD src0_sel:WORD_1
	v_cvt_f32_f16_e32 v236, v185
	v_pk_mov_b32 v[188:189], v[130:131], v[130:131] op_sel:[1,0]
	v_pk_mov_b32 v[186:187], v[38:39], v[38:39] op_sel:[1,0]
	v_mov_b32_e32 v129, v189
	v_cvt_f32_f16_sdwa v173, v174 dst_sel:DWORD dst_unused:UNUSED_PAD src0_sel:WORD_1
	v_cvt_f32_f16_e32 v172, v174
	v_mov_b32_e32 v33, v187
	v_mov_b32_e32 v187, v155
	v_mov_b32_e32 v189, v166
	v_cvt_f32_f16_sdwa v221, v175 dst_sel:DWORD dst_unused:UNUSED_PAD src0_sel:WORD_1
	v_cvt_f32_f16_e32 v220, v175
	v_cvt_f32_f16_sdwa v175, v176 dst_sel:DWORD dst_unused:UNUSED_PAD src0_sel:WORD_1
	v_cvt_f32_f16_e32 v174, v176
	v_cvt_f32_f16_sdwa v229, v177 dst_sel:DWORD dst_unused:UNUSED_PAD src0_sel:WORD_1
	v_cvt_f32_f16_e32 v228, v177
	v_cvt_f32_f16_sdwa v177, v178 dst_sel:DWORD dst_unused:UNUSED_PAD src0_sel:WORD_1
	v_cvt_f32_f16_e32 v176, v178
	v_cvt_f32_f16_sdwa v231, v179 dst_sel:DWORD dst_unused:UNUSED_PAD src0_sel:WORD_1
	v_cvt_f32_f16_e32 v230, v179
	v_cvt_f32_f16_sdwa v179, v180 dst_sel:DWORD dst_unused:UNUSED_PAD src0_sel:WORD_1
	v_cvt_f32_f16_e32 v178, v180
	v_cvt_f32_f16_sdwa v181, v182 dst_sel:DWORD dst_unused:UNUSED_PAD src0_sel:WORD_1
	v_cvt_f32_f16_e32 v180, v182
	v_cvt_f32_f16_sdwa v235, v183 dst_sel:DWORD dst_unused:UNUSED_PAD src0_sel:WORD_1
	v_cvt_f32_f16_e32 v234, v183
	v_cvt_f32_f16_sdwa v183, v184 dst_sel:DWORD dst_unused:UNUSED_PAD src0_sel:WORD_1
	v_cvt_f32_f16_e32 v182, v184
	v_pk_fma_f32 v[184:185], v[192:193], v[128:129], v[216:217] neg_lo:[1,0,0] neg_hi:[1,0,0]
	v_cvt_f32_f16_sdwa v7, v10 dst_sel:DWORD dst_unused:UNUSED_PAD src0_sel:WORD_1
	v_cvt_f32_f16_e32 v6, v10
	v_pk_fma_f32 v[10:11], v[192:193], v[186:187], v[214:215] neg_lo:[1,0,0] neg_hi:[1,0,0]
	v_pk_fma_f32 v[186:187], v[192:193], v[188:189], v[218:219] neg_lo:[1,0,0] neg_hi:[1,0,0]
	v_pk_fma_f32 v[172:173], v[192:193], v[122:123], v[172:173] neg_lo:[1,0,0] neg_hi:[1,0,0]
	v_pk_mul_f32 v[214:215], v[186:187], v[186:187]
	v_pk_mul_f32 v[216:217], v[172:173], v[172:173]
	v_pk_fma_f32 v[188:189], v[192:193], v[190:191], v[220:221] neg_lo:[1,0,0] neg_hi:[1,0,0]
	v_pk_fma_f32 v[174:175], v[192:193], v[106:107], v[174:175] neg_lo:[1,0,0] neg_hi:[1,0,0]
	v_pk_mul_f32 v[218:219], v[188:189], v[188:189]
	v_pk_mul_f32 v[220:221], v[174:175], v[174:175]
	v_pk_fma_f32 v[190:191], v[192:193], v[194:195], v[228:229] neg_lo:[1,0,0] neg_hi:[1,0,0]
	v_pk_fma_f32 v[176:177], v[192:193], v[80:81], v[176:177] neg_lo:[1,0,0] neg_hi:[1,0,0]
	v_pk_mul_f32 v[228:229], v[190:191], v[190:191]
	v_pk_fma_f32 v[194:195], v[192:193], v[202:203], v[230:231] neg_lo:[1,0,0] neg_hi:[1,0,0]
	v_pk_mul_f32 v[230:231], v[176:177], v[176:177]
	v_pk_fma_f32 v[178:179], v[192:193], v[50:51], v[178:179] neg_lo:[1,0,0] neg_hi:[1,0,0]
	v_pk_fma_f32 v[202:203], v[192:193], v[210:211], v[234:235] neg_lo:[1,0,0] neg_hi:[1,0,0]
	v_pk_mul_f32 v[234:235], v[178:179], v[178:179]
	v_pk_fma_f32 v[180:181], v[192:193], v[44:45], v[180:181] neg_lo:[1,0,0] neg_hi:[1,0,0]
	v_pk_mul_f32 v[240:241], v[202:203], v[202:203]
	v_pk_mul_f32 v[238:239], v[180:181], v[180:181]
	v_pk_fma_f32 v[182:183], v[192:193], v[36:37], v[182:183] neg_lo:[1,0,0] neg_hi:[1,0,0]
	v_pk_fma_f32 v[6:7], v[192:193], v[32:33], v[6:7] neg_lo:[1,0,0] neg_hi:[1,0,0]
	v_pk_mul_f32 v[242:243], v[182:183], v[182:183]
	v_pk_mul_f32 v[210:211], v[10:11], v[10:11]
	v_mov_b32_e32 v33, v224
	s_waitcnt vmcnt(0)
	v_pk_mul_f32 v[132:133], v[168:169], v[132:133]
	v_pk_mul_f32 v[134:135], v[170:171], v[134:135]
	v_cvt_pk_f16_f32 v132, v132, v133
	v_cvt_pk_f16_f32 v133, v134, v135
	global_store_dwordx2 v[248:249], v[132:133], off offset:2272
	global_load_dwordx4 v[168:171], v[200:201], off
	v_pk_fma_f32 v[134:135], v[192:193], v[204:205], v[232:233] neg_lo:[1,0,0] neg_hi:[1,0,0]
	v_pk_fma_f32 v[204:205], v[192:193], v[212:213], v[236:237] neg_lo:[1,0,0] neg_hi:[1,0,0]
	v_pk_mul_f32 v[212:213], v[184:185], v[184:185]
	v_pk_mul_f32 v[232:233], v[194:195], v[194:195]
	v_add_f32_e32 v15, v212, v213
	v_add_f32_e32 v15, v214, v15
	v_add_f32_e32 v15, v215, v15
	v_add_f32_e32 v15, v216, v15
	v_add_f32_e32 v15, v217, v15
	v_add_f32_e32 v15, v218, v15
	v_add_f32_e32 v15, v219, v15
	v_add_f32_e32 v15, v220, v15
	v_add_f32_e32 v15, v221, v15
	v_add_f32_e32 v15, v228, v15
	v_add_f32_e32 v15, v229, v15
	v_add_f32_e32 v15, v230, v15
	v_add_f32_e32 v15, v231, v15
	v_add_f32_e32 v15, v232, v15
	v_add_f32_e32 v15, v233, v15
	v_add_f32_e32 v15, v234, v15
	v_pk_mul_f32 v[236:237], v[134:135], v[134:135]
	v_add_f32_e32 v15, v235, v15
	v_add_f32_e32 v15, v236, v15
	v_add_f32_e32 v15, v237, v15
	v_add_f32_e32 v15, v238, v15
	v_add_f32_e32 v15, v239, v15
	v_add_f32_e32 v15, v240, v15
	v_add_f32_e32 v15, v241, v15
	v_add_f32_e32 v15, v242, v15
	v_pk_mul_f32 v[244:245], v[204:205], v[204:205]
	v_add_f32_e32 v15, v243, v15
	v_add_f32_e32 v15, v244, v15
	v_pk_mul_f32 v[132:133], v[6:7], v[6:7]
	v_add_f32_e32 v15, v245, v15
	v_add_f32_e32 v15, v132, v15
	v_add_f32_e32 v15, v133, v15
	v_add_f32_e32 v15, v210, v15
	v_add_f32_e32 v15, v211, v15
	ds_swizzle_b32 v19, v15 offset:swizzle(SWAP,16)
	v_lshlrev_b32_e32 v9, 2, v9
	v_bitop3_b32 v9, v9, s3, v226 bitop3:0x6c
	v_pk_mov_b32 v[210:211], v[4:5], v[4:5] op_sel:[1,0]
	s_waitcnt lgkmcnt(0)
	v_add_f32_e32 v15, v15, v19
	ds_bpermute_b32 v9, v9, v15
	s_waitcnt lgkmcnt(0)
; __device__ __forceinline__ void attn_phase(const Params& p, char* smem, int coff) {
;     ...
;             for (int j = 0; j < 4; ++j) { float o = (float)o0[j] - lam * oacc[md][nq][j]; oacc[md][nq][j] = o; ss += o * o; }
;           }
;           ss += shx(ss, 16); ss += shx(ss, 32);
;           const float r = rsqrtf(ss * (1.f / 128.f) + 1e-5f) * (1.f - 0.35550906759f);
; #pragma unroll
;           for (int md = 0; md < 8; ++md) {
;             f4 gg = *(const f4*)(p.in[41] + md * 16 + fq * 4); h4 o;
; #pragma unroll
;             for (int j = 0; j < 4; ++j) o[j] = (hf)(oacc[md][nq][j] * r * gg[j]);
;             *(h4*)(dst + md * 16) = o;
	v_add_f32_e32 v9, v15, v9
	v_fmamk_f32 v9, v9, 0x3c000000, v55
	v_mul_f32_e32 v15, 0x4b800000, v9
	v_cmp_gt_f32_e32 vcc, s83, v9
	s_nop 1
	v_cndmask_b32_e32 v9, v9, v15, vcc
	v_rsq_f32_e32 v9, v9
	s_nop 0
	v_mul_f32_e32 v15, 0x45800000, v9
	v_cndmask_b32_e32 v9, v9, v15, vcc
	v_mul_f32_e32 v132, 0x3f24fd5c, v9
	v_pk_mul_f32 v[184:185], v[184:185], v[132:133] op_sel_hi:[1,0]
	v_pk_mul_f32 v[186:187], v[186:187], v[132:133] op_sel_hi:[1,0]
	v_pk_mul_f32 v[172:173], v[172:173], v[132:133] op_sel_hi:[1,0]
	v_pk_mul_f32 v[134:135], v[134:135], v[132:133] op_sel_hi:[1,0]
	v_pk_mul_f32 v[182:183], v[182:183], v[132:133] op_sel_hi:[1,0]
	v_pk_mul_f32 v[6:7], v[6:7], v[132:133] op_sel_hi:[1,0]
	v_pk_mul_f32 v[10:11], v[10:11], v[132:133] op_sel_hi:[1,0]
	v_mov_b32_e32 v9, v211
	v_mov_b32_e32 v211, v137
	s_waitcnt vmcnt(0)
	v_pk_mul_f32 v[168:169], v[168:169], v[184:185]
	v_pk_mul_f32 v[170:171], v[170:171], v[186:187]
	v_cvt_pk_f16_f32 v168, v168, v169
	v_cvt_pk_f16_f32 v169, v170, v171
	global_store_dwordx2 v[206:207], v[168:169], off offset:2048
	global_load_dwordx4 v[168:171], v[200:201], off offset:64
	v_pk_mul_f32 v[184:185], v[188:189], v[132:133] op_sel_hi:[1,0]
	v_pk_mul_f32 v[188:189], v[204:205], v[132:133] op_sel_hi:[1,0]
	v_pk_mov_b32 v[204:205], v[12:13], v[12:13] op_sel:[1,0]
	s_waitcnt vmcnt(0)
	v_pk_mul_f32 v[168:169], v[168:169], v[172:173]
	v_pk_mul_f32 v[170:171], v[170:171], v[184:185]
	v_cvt_pk_f16_f32 v168, v168, v169
	v_cvt_pk_f16_f32 v169, v170, v171
	global_store_dwordx2 v[206:207], v[168:169], off offset:2080
	global_load_dwordx4 v[168:171], v[200:201], off offset:128
	v_pk_mul_f32 v[172:173], v[174:175], v[132:133] op_sel_hi:[1,0]
	v_pk_mul_f32 v[174:175], v[190:191], v[132:133] op_sel_hi:[1,0]
	v_mov_b32_e32 v15, v205
	v_mov_b32_e32 v205, v140
	v_pk_mov_b32 v[190:191], v[24:25], v[24:25] op_sel:[1,0]
	s_waitcnt vmcnt(0)
	v_pk_mul_f32 v[168:169], v[168:169], v[172:173]
	v_pk_mul_f32 v[170:171], v[170:171], v[174:175]
	v_cvt_pk_f16_f32 v168, v168, v169
	v_cvt_pk_f16_f32 v169, v170, v171
	global_store_dwordx2 v[206:207], v[168:169], off offset:2112
	global_load_dwordx4 v[168:171], v[200:201], off offset:192
	v_pk_mul_f32 v[172:173], v[176:177], v[132:133] op_sel_hi:[1,0]
	v_pk_mul_f32 v[174:175], v[194:195], v[132:133] op_sel_hi:[1,0]
	v_mov_b32_e32 v27, v191
	v_mov_b32_e32 v191, v159
	v_pk_mov_b32 v[194:195], v[20:21], v[20:21] op_sel:[1,0]
	s_waitcnt vmcnt(0)
	v_pk_mul_f32 v[168:169], v[168:169], v[172:173]
	v_pk_mul_f32 v[170:171], v[170:171], v[174:175]
	v_cvt_pk_f16_f32 v168, v168, v169
	v_cvt_pk_f16_f32 v169, v170, v171
	global_store_dwordx2 v[206:207], v[168:169], off offset:2144
	global_load_dwordx4 v[168:171], v[200:201], off offset:256
	v_pk_mul_f32 v[172:173], v[178:179], v[132:133] op_sel_hi:[1,0]
	v_mov_b32_e32 v23, v195
	v_mov_b32_e32 v195, v149
	s_waitcnt vmcnt(0)
	v_pk_mul_f32 v[168:169], v[168:169], v[172:173]
	v_pk_mul_f32 v[134:135], v[170:171], v[134:135]
	v_cvt_pk_f16_f32 v168, v168, v169
	v_cvt_pk_f16_f32 v169, v134, v135
	global_store_dwordx2 v[206:207], v[168:169], off offset:2176
	global_load_dwordx4 v[168:171], v[200:201], off offset:320
	v_pk_mul_f32 v[134:135], v[180:181], v[132:133] op_sel_hi:[1,0]
	v_pk_mul_f32 v[172:173], v[202:203], v[132:133] op_sel_hi:[1,0]
	v_pk_mov_b32 v[202:203], v[16:17], v[16:17] op_sel:[1,0]
	s_waitcnt vmcnt(0)
	v_pk_mul_f32 v[134:135], v[168:169], v[134:135]
	v_pk_mul_f32 v[168:169], v[170:171], v[172:173]
	v_cvt_pk_f16_f32 v134, v134, v135
	v_cvt_pk_f16_f32 v135, v168, v169
	global_store_dwordx2 v[206:207], v[134:135], off offset:2208
	global_load_dwordx4 v[168:171], v[200:201], off offset:384
	s_nop 0
	global_load_dwordx2 v[134:135], v[208:209], off offset:2272
	global_load_dwordx2 v[172:173], v[208:209], off offset:2048
	global_load_dwordx2 v[174:175], v[208:209], off offset:2080
	global_load_dwordx2 v[176:177], v[208:209], off offset:2112
	global_load_dwordx2 v[178:179], v[208:209], off offset:2144
	global_load_dwordx2 v[180:181], v[208:209], off offset:2176
	global_load_dwordx2 v[184:185], v[208:209], off offset:2208
	global_load_dwordx2 v[186:187], v[208:209], off offset:2240
	v_mov_b32_e32 v19, v203
	v_mov_b32_e32 v203, v144
	s_waitcnt vmcnt(8)
	v_pk_mul_f32 v[168:169], v[168:169], v[182:183]
	v_pk_mul_f32 v[170:171], v[170:171], v[188:189]
	v_cvt_pk_f16_f32 v168, v168, v169
	v_cvt_pk_f16_f32 v169, v170, v171
	global_store_dwordx2 v[206:207], v[168:169], off offset:2240
	global_load_dwordx4 v[168:171], v[200:201], off offset:448
	s_waitcnt vmcnt(9)
	v_cvt_f32_f16_sdwa v133, v134 dst_sel:DWORD dst_unused:UNUSED_PAD src0_sel:WORD_1
	v_cvt_f32_f16_e32 v132, v134
	v_cvt_f32_f16_sdwa v213, v135 dst_sel:DWORD dst_unused:UNUSED_PAD src0_sel:WORD_1
	v_cvt_f32_f16_e32 v212, v135
	s_waitcnt vmcnt(8)
	v_cvt_f32_f16_sdwa v135, v172 dst_sel:DWORD dst_unused:UNUSED_PAD src0_sel:WORD_1
	v_cvt_f32_f16_e32 v134, v172
	v_pk_mov_b32 v[182:183], v[46:47], v[46:47] op_sel:[1,0]
	v_cvt_f32_f16_sdwa v215, v173 dst_sel:DWORD dst_unused:UNUSED_PAD src0_sel:WORD_1
	v_mov_b32_e32 v35, v183
	v_cvt_f32_f16_e32 v214, v173
	s_waitcnt vmcnt(7)
	v_cvt_f32_f16_sdwa v173, v174 dst_sel:DWORD dst_unused:UNUSED_PAD src0_sel:WORD_1
	v_cvt_f32_f16_e32 v172, v174
	v_cvt_f32_f16_sdwa v217, v175 dst_sel:DWORD dst_unused:UNUSED_PAD src0_sel:WORD_1
	v_cvt_f32_f16_e32 v216, v175
	s_waitcnt vmcnt(6)
	v_cvt_f32_f16_sdwa v175, v176 dst_sel:DWORD dst_unused:UNUSED_PAD src0_sel:WORD_1
	v_cvt_f32_f16_e32 v174, v176
	v_cvt_f32_f16_sdwa v219, v177 dst_sel:DWORD dst_unused:UNUSED_PAD src0_sel:WORD_1
	v_cvt_f32_f16_e32 v218, v177
	s_waitcnt vmcnt(5)
; __device__ __forceinline__ void attn_phase(const Params& p, char* smem, int coff) {
;     ...
; #pragma unroll
;         for (int nq = 0; nq < 4; ++nq) {
;           hf* dst = mix + (size_t)(s0 + q0 + wv * 64 + nq * 16 + fr) * 2048 + 1024 + h * 128 + fq * 4;
;           float ss = 0.f;
; #pragma unroll
;           for (int md = 0; md < 8; ++md) {
;             h4 o0 = *(const h4*)(dst + md * 16);
; #pragma unroll
;             for (int j = 0; j < 4; ++j) { float o = (float)o0[j] - lam * oacc[md][nq][j]; oacc[md][nq][j] = o; ss += o * o; }
;           }
;           ss += shx(ss, 16); ss += shx(ss, 32);
;           const float r = rsqrtf(ss * (1.f / 128.f) + 1e-5f) * (1.f - 0.35550906759f);
; #pragma unroll
;           for (int md = 0; md < 8; ++md) {
;             f4 gg = *(const f4*)(p.in[41] + md * 16 + fq * 4); h4 o;
; #pragma unroll
;             for (int j = 0; j < 4; ++j) o[j] = (hf)(oacc[md][nq][j] * r * gg[j]);
;             *(h4*)(dst + md * 16) = o;
	v_cvt_f32_f16_sdwa v177, v178 dst_sel:DWORD dst_unused:UNUSED_PAD src0_sel:WORD_1
	v_cvt_f32_f16_e32 v176, v178
	v_cvt_f32_f16_sdwa v221, v179 dst_sel:DWORD dst_unused:UNUSED_PAD src0_sel:WORD_1
	v_cvt_f32_f16_e32 v220, v179
	s_waitcnt vmcnt(4)
	v_cvt_f32_f16_sdwa v179, v180 dst_sel:DWORD dst_unused:UNUSED_PAD src0_sel:WORD_1
	v_cvt_f32_f16_e32 v178, v180
	v_cvt_f32_f16_sdwa v229, v181 dst_sel:DWORD dst_unused:UNUSED_PAD src0_sel:WORD_1
	v_cvt_f32_f16_e32 v228, v181
	s_waitcnt vmcnt(3)
	v_cvt_f32_f16_sdwa v181, v184 dst_sel:DWORD dst_unused:UNUSED_PAD src0_sel:WORD_1
	v_cvt_f32_f16_e32 v180, v184
	v_cvt_f32_f16_sdwa v231, v185 dst_sel:DWORD dst_unused:UNUSED_PAD src0_sel:WORD_1
	v_cvt_f32_f16_e32 v230, v185
	s_waitcnt vmcnt(2)
	v_cvt_f32_f16_sdwa v185, v186 dst_sel:DWORD dst_unused:UNUSED_PAD src0_sel:WORD_1
	v_cvt_f32_f16_e32 v184, v186
	v_cvt_f32_f16_sdwa v233, v187 dst_sel:DWORD dst_unused:UNUSED_PAD src0_sel:WORD_1
	v_cvt_f32_f16_e32 v232, v187
	v_pk_fma_f32 v[186:187], v[192:193], v[0:1], v[132:133] neg_lo:[1,0,0] neg_hi:[1,0,0]
	v_pk_fma_f32 v[234:235], v[192:193], v[34:35], v[134:135] neg_lo:[1,0,0] neg_hi:[1,0,0]
	v_mov_b32_e32 v183, v167
	v_pk_mov_b32 v[188:189], v[28:29], v[28:29] op_sel:[1,0]
	v_pk_fma_f32 v[182:183], v[192:193], v[182:183], v[214:215] neg_lo:[1,0,0] neg_hi:[1,0,0]
	v_mov_b32_e32 v31, v189
	v_pk_fma_f32 v[212:213], v[192:193], v[2:3], v[212:213] neg_lo:[1,0,0] neg_hi:[1,0,0]
	v_pk_fma_f32 v[172:173], v[192:193], v[30:31], v[172:173] neg_lo:[1,0,0] neg_hi:[1,0,0]
	v_mov_b32_e32 v189, v165
	v_pk_mul_f32 v[214:215], v[172:173], v[172:173]
	v_pk_fma_f32 v[188:189], v[192:193], v[188:189], v[216:217] neg_lo:[1,0,0] neg_hi:[1,0,0]
	v_pk_fma_f32 v[174:175], v[192:193], v[26:27], v[174:175] neg_lo:[1,0,0] neg_hi:[1,0,0]
	v_pk_mul_f32 v[216:217], v[188:189], v[188:189]
	v_pk_fma_f32 v[190:191], v[192:193], v[190:191], v[218:219] neg_lo:[1,0,0] neg_hi:[1,0,0]
	v_pk_mul_f32 v[218:219], v[174:175], v[174:175]
	v_pk_fma_f32 v[194:195], v[192:193], v[194:195], v[220:221] neg_lo:[1,0,0] neg_hi:[1,0,0]
	v_pk_mul_f32 v[220:221], v[190:191], v[190:191]
	v_pk_fma_f32 v[176:177], v[192:193], v[22:23], v[176:177] neg_lo:[1,0,0] neg_hi:[1,0,0]
	v_pk_fma_f32 v[178:179], v[192:193], v[18:19], v[178:179] neg_lo:[1,0,0] neg_hi:[1,0,0]
	s_waitcnt vmcnt(0)
	v_pk_mul_f32 v[6:7], v[168:169], v[6:7]
	v_pk_mul_f32 v[10:11], v[170:171], v[10:11]
	v_cvt_pk_f16_f32 v6, v6, v7
	v_cvt_pk_f16_f32 v7, v10, v11
	global_store_dwordx2 v[206:207], v[6:7], off offset:2272
	global_load_dwordx4 v[132:135], v[200:201], off
	v_pk_fma_f32 v[168:169], v[192:193], v[204:205], v[230:231] neg_lo:[1,0,0] neg_hi:[1,0,0]
	v_pk_mul_f32 v[204:205], v[234:235], v[234:235]
	v_pk_fma_f32 v[10:11], v[192:193], v[14:15], v[180:181] neg_lo:[1,0,0] neg_hi:[1,0,0]
	v_pk_fma_f32 v[180:181], v[192:193], v[210:211], v[232:233] neg_lo:[1,0,0] neg_hi:[1,0,0]
	v_pk_mul_f32 v[210:211], v[182:183], v[182:183]
	v_add_f32_e32 v3, v204, v205
	v_add_f32_e32 v3, v210, v3
	v_add_f32_e32 v3, v211, v3
	v_add_f32_e32 v3, v214, v3
	v_add_f32_e32 v3, v215, v3
	v_add_f32_e32 v3, v216, v3
	v_add_f32_e32 v3, v217, v3
	v_add_f32_e32 v3, v218, v3
	v_add_f32_e32 v3, v219, v3
	v_add_f32_e32 v3, v220, v3
	v_pk_fma_f32 v[6:7], v[192:193], v[202:203], v[228:229] neg_lo:[1,0,0] neg_hi:[1,0,0]
	v_pk_mul_f32 v[228:229], v[176:177], v[176:177]
	v_add_f32_e32 v3, v221, v3
	v_add_f32_e32 v3, v228, v3
	v_pk_mul_f32 v[230:231], v[194:195], v[194:195]
	v_add_f32_e32 v3, v229, v3
	v_add_f32_e32 v3, v230, v3
	v_pk_mul_f32 v[232:233], v[178:179], v[178:179]
	v_add_f32_e32 v3, v231, v3
	v_add_f32_e32 v3, v232, v3
	v_pk_mul_f32 v[236:237], v[6:7], v[6:7]
	v_add_f32_e32 v3, v233, v3
	v_add_f32_e32 v3, v236, v3
	v_pk_mul_f32 v[238:239], v[10:11], v[10:11]
	v_add_f32_e32 v3, v237, v3
	v_add_f32_e32 v3, v238, v3
	v_pk_mul_f32 v[240:241], v[168:169], v[168:169]
	v_add_f32_e32 v3, v239, v3
	v_pk_fma_f32 v[170:171], v[192:193], v[8:9], v[184:185] neg_lo:[1,0,0] neg_hi:[1,0,0]
	v_add_f32_e32 v3, v240, v3
	v_pk_mul_f32 v[242:243], v[170:171], v[170:171]
	v_add_f32_e32 v3, v241, v3
	v_add_f32_e32 v3, v242, v3
	v_pk_mul_f32 v[244:245], v[180:181], v[180:181]
	v_add_f32_e32 v3, v243, v3
	v_add_f32_e32 v3, v244, v3
	v_pk_mul_f32 v[184:185], v[186:187], v[186:187]
	v_add_f32_e32 v3, v245, v3
	v_add_f32_e32 v3, v184, v3
	v_pk_mul_f32 v[202:203], v[212:213], v[212:213]
	v_add_f32_e32 v3, v185, v3
	v_add_f32_e32 v3, v202, v3
	v_add_f32_e32 v3, v203, v3
	ds_swizzle_b32 v9, v3 offset:swizzle(SWAP,16)
	s_waitcnt lgkmcnt(0)
; __device__ __forceinline__ void attn_phase(const Params& p, char* smem, int coff) {
;     ...
;             for (int j = 0; j < 4; ++j) { float o = (float)o0[j] - lam * oacc[md][nq][j]; oacc[md][nq][j] = o; ss += o * o; }
;           }
;           ss += shx(ss, 16); ss += shx(ss, 32);
;           const float r = rsqrtf(ss * (1.f / 128.f) + 1e-5f) * (1.f - 0.35550906759f);
; #pragma unroll
;           for (int md = 0; md < 8; ++md) {
;             f4 gg = *(const f4*)(p.in[41] + md * 16 + fq * 4); h4 o;
; #pragma unroll
;             for (int j = 0; j < 4; ++j) o[j] = (hf)(oacc[md][nq][j] * r * gg[j]);
;             *(h4*)(dst + md * 16) = o;
;           }
;         }
;       }
;     }
	v_add_f32_e32 v3, v3, v9
	v_lshlrev_b32_e32 v9, 2, v33
	v_bitop3_b32 v9, v9, s3, v226 bitop3:0x6c
	ds_bpermute_b32 v9, v9, v3
	s_waitcnt lgkmcnt(0)
	v_add_f32_e32 v3, v3, v9
	v_fmamk_f32 v3, v3, 0x3c000000, v55
	v_mul_f32_e32 v9, 0x4b800000, v3
	v_cmp_gt_f32_e32 vcc, s83, v3
	s_nop 1
	v_cndmask_b32_e32 v3, v3, v9, vcc
	v_rsq_f32_e32 v3, v3
	s_nop 0
	v_mul_f32_e32 v9, 0x45800000, v3
	v_cndmask_b32_e32 v3, v3, v9, vcc
	v_mul_f32_e32 v136, 0x3f24fd5c, v3
	v_pk_mul_f32 v[184:185], v[234:235], v[136:137] op_sel_hi:[1,0]
	v_pk_mul_f32 v[182:183], v[182:183], v[136:137] op_sel_hi:[1,0]
	v_pk_mul_f32 v[172:173], v[172:173], v[136:137] op_sel_hi:[1,0]
	v_pk_mul_f32 v[6:7], v[6:7], v[136:137] op_sel_hi:[1,0]
	s_waitcnt vmcnt(0)
	v_pk_mul_f32 v[132:133], v[132:133], v[184:185]
	v_pk_mul_f32 v[134:135], v[134:135], v[182:183]
	v_cvt_pk_f16_f32 v132, v132, v133
	v_cvt_pk_f16_f32 v133, v134, v135
	global_store_dwordx2 v[208:209], v[132:133], off offset:2048
	global_load_dwordx4 v[132:135], v[200:201], off offset:64
	v_pk_mul_f32 v[182:183], v[188:189], v[136:137] op_sel_hi:[1,0]
	v_mul_f32_e32 v3, v212, v136
	v_mul_f32_e32 v9, v213, v136
	s_waitcnt vmcnt(0)
	v_pk_mul_f32 v[132:133], v[132:133], v[172:173]
	v_pk_mul_f32 v[134:135], v[134:135], v[182:183]
	v_cvt_pk_f16_f32 v132, v132, v133
	v_cvt_pk_f16_f32 v133, v134, v135
	global_store_dwordx2 v[208:209], v[132:133], off offset:2080
	global_load_dwordx4 v[132:135], v[200:201], off offset:128
	v_pk_mul_f32 v[172:173], v[174:175], v[136:137] op_sel_hi:[1,0]
	v_pk_mul_f32 v[174:175], v[190:191], v[136:137] op_sel_hi:[1,0]
	s_waitcnt vmcnt(0)
	v_pk_mul_f32 v[132:133], v[132:133], v[172:173]
	v_pk_mul_f32 v[134:135], v[134:135], v[174:175]
	v_cvt_pk_f16_f32 v132, v132, v133
	v_cvt_pk_f16_f32 v133, v134, v135
	global_store_dwordx2 v[208:209], v[132:133], off offset:2112
	global_load_dwordx4 v[132:135], v[200:201], off offset:192
	v_pk_mul_f32 v[172:173], v[176:177], v[136:137] op_sel_hi:[1,0]
	v_pk_mul_f32 v[174:175], v[194:195], v[136:137] op_sel_hi:[1,0]
	s_waitcnt vmcnt(0)
	v_pk_mul_f32 v[132:133], v[132:133], v[172:173]
	v_pk_mul_f32 v[134:135], v[134:135], v[174:175]
	v_cvt_pk_f16_f32 v132, v132, v133
	v_cvt_pk_f16_f32 v133, v134, v135
	global_store_dwordx2 v[208:209], v[132:133], off offset:2144
	global_load_dwordx4 v[132:135], v[200:201], off offset:256
	v_pk_mul_f32 v[172:173], v[178:179], v[136:137] op_sel_hi:[1,0]
	s_waitcnt vmcnt(0)
	v_pk_mul_f32 v[6:7], v[134:135], v[6:7]
	v_pk_mul_f32 v[132:133], v[132:133], v[172:173]
	s_nop 0
	v_cvt_pk_f16_f32 v132, v132, v133
	v_cvt_pk_f16_f32 v133, v6, v7
	global_store_dwordx2 v[208:209], v[132:133], off offset:2176
	global_load_dwordx4 v[132:135], v[200:201], off offset:320
	v_pk_mul_f32 v[6:7], v[10:11], v[136:137] op_sel_hi:[1,0]
	v_pk_mul_f32 v[10:11], v[168:169], v[136:137] op_sel_hi:[1,0]
	s_waitcnt vmcnt(0)
	v_pk_mul_f32 v[6:7], v[132:133], v[6:7]
	v_pk_mul_f32 v[10:11], v[134:135], v[10:11]
	v_cvt_pk_f16_f32 v6, v6, v7
	v_cvt_pk_f16_f32 v7, v10, v11
	global_store_dwordx2 v[208:209], v[6:7], off offset:2208
	global_load_dwordx4 v[132:135], v[200:201], off offset:384
	v_pk_mul_f32 v[6:7], v[170:171], v[136:137] op_sel_hi:[1,0]
	v_pk_mul_f32 v[10:11], v[180:181], v[136:137] op_sel_hi:[1,0]
	s_waitcnt vmcnt(0)
	v_pk_mul_f32 v[6:7], v[132:133], v[6:7]
	v_pk_mul_f32 v[10:11], v[134:135], v[10:11]
	v_cvt_pk_f16_f32 v6, v6, v7
	v_cvt_pk_f16_f32 v7, v10, v11
	global_store_dwordx2 v[208:209], v[6:7], off offset:2240
	global_load_dwordx4 v[132:135], v[200:201], off offset:448
	v_pk_mul_f32 v[6:7], v[186:187], v[136:137] op_sel_hi:[1,0]
	s_waitcnt vmcnt(0)
	v_fma_mixlo_f16 v10, v134, v3, 0
	v_pk_mul_f32 v[6:7], v[132:133], v[6:7]
	v_mul_f32_e32 v3, v135, v9
	v_cvt_pk_f16_f32 v6, v6, v7
	v_pack_b32_f16 v7, v10, 0
	s_cbranch_execnz .LBB0_1946
	s_branch .LBB0_1945
